# phase 0 adaLN modulation GEMV: weight loads software-pipelined (32 in flight) and silu pre-pass loads batched by 8; arithmetic order unchanged
# speedup vs baseline: 1.0122x; 1.0122x over previous
.LBB0_19:
	global_load_dword v2, v[10:11], off
	global_load_dword v21, v[10:11], off offset:1024
	global_load_dword v23, v[10:11], off offset:2048
	global_load_dword v25, v[12:13], off
	v_readlane_b32 s52, v241, 18
	s_mov_b64 s[30:31], 0
	v_mov_b32_e32 v19, v56
	v_readlane_b32 s64, v241, 30
	v_readlane_b32 s65, v241, 31
	v_readlane_b32 s53, v241, 19
	v_readlane_b32 s54, v241, 20
	v_readlane_b32 s55, v241, 21
	v_readlane_b32 s56, v241, 22
	v_readlane_b32 s57, v241, 23
	v_readlane_b32 s58, v241, 24
	v_readlane_b32 s59, v241, 25
	v_readlane_b32 s60, v241, 26
	v_readlane_b32 s61, v241, 27
	v_readlane_b32 s62, v241, 28
	v_readlane_b32 s63, v241, 29
	v_readlane_b32 s66, v241, 32
	v_readlane_b32 s67, v241, 33
	s_waitcnt vmcnt(3)
	v_mul_f32_e32 v27, 0xbfb8aa3b, v2
	s_waitcnt vmcnt(2)
	v_mul_f32_e32 v29, 0xbfb8aa3b, v21
	v_exp_f32_e32 v27, v27
	s_waitcnt vmcnt(1)
	v_mul_f32_e32 v31, 0xbfb8aa3b, v23
	v_exp_f32_e32 v29, v29
	s_waitcnt vmcnt(0)
	v_mul_f32_e32 v33, 0xbfb8aa3b, v25
	v_exp_f32_e32 v31, v31
	v_exp_f32_e32 v33, v33
	v_add_f32_e32 v27, 1.0, v27
	v_add_f32_e32 v29, 1.0, v29
	v_add_f32_e32 v31, 1.0, v31
	v_add_f32_e32 v33, 1.0, v33
	s_mov_b64 vcc, s[2:3]
	v_rcp_f32_e32 v35, v27
	s_nop 0
	v_mul_f32_e32 v2, v2, v35
	s_mov_b64 vcc, s[4:5]
	v_rcp_f32_e32 v27, v29
	s_nop 0
	v_mul_f32_e32 v21, v21, v27
	s_mov_b64 vcc, s[6:7]
	ds_write2st64_b32 v51, v2, v21 offset1:4
	v_rcp_f32_e32 v27, v31
	s_nop 0
	v_mul_f32_e32 v2, v23, v27
	ds_write_b32 v51, v2 offset:2048
	v_rcp_f32_e32 v21, v33
	s_nop 0
	v_mul_f32_e32 v2, v25, v21
	v_mov_b32_e32 v21, v55
	ds_write_b32 v52, v2
	v_add_u32_e32 v2, 0x200, v19
	v_and_b32_e32 v2, 0x3fff, v2
	v_add_u32_e32 v2, 0xfffffc00, v2
	v_lshl_add_u64 v[126:127], v[2:3], 2, s[64:65]
	global_load_dword v118, v[126:127], off
	v_add_u32_e32 v2, 0x300, v19
	v_and_b32_e32 v2, 0x3fff, v2
	v_add_u32_e32 v2, 0xfffffc00, v2
	v_lshl_add_u64 v[128:129], v[2:3], 2, s[64:65]
	global_load_dword v119, v[128:129], off
	v_add_u32_e32 v2, 0x400, v19
	v_and_b32_e32 v2, 0x3fff, v2
	v_add_u32_e32 v2, 0xfffffc00, v2
	v_lshl_add_u64 v[130:131], v[2:3], 2, s[64:65]
	global_load_dword v120, v[130:131], off
	v_add_u32_e32 v2, 0x500, v19
	v_and_b32_e32 v2, 0x3fff, v2
	v_add_u32_e32 v2, 0xfffffc00, v2
	v_lshl_add_u64 v[132:133], v[2:3], 2, s[64:65]
	global_load_dword v121, v[132:133], off
	v_add_u32_e32 v2, 0x600, v19
	v_and_b32_e32 v2, 0x3fff, v2
	v_add_u32_e32 v2, 0xfffffc00, v2
	v_lshl_add_u64 v[134:135], v[2:3], 2, s[64:65]
	global_load_dword v122, v[134:135], off
	v_add_u32_e32 v2, 0x700, v19
	v_and_b32_e32 v2, 0x3fff, v2
	v_add_u32_e32 v2, 0xfffffc00, v2
	v_lshl_add_u64 v[136:137], v[2:3], 2, s[64:65]
	global_load_dword v123, v[136:137], off
	v_add_u32_e32 v2, 0x800, v19
	v_and_b32_e32 v2, 0x3fff, v2
	v_add_u32_e32 v2, 0xfffffc00, v2
	v_lshl_add_u64 v[138:139], v[2:3], 2, s[64:65]
	global_load_dword v124, v[138:139], off
	v_add_u32_e32 v2, 0x900, v19
	v_and_b32_e32 v2, 0x3fff, v2
	v_add_u32_e32 v2, 0xfffffc00, v2
	v_lshl_add_u64 v[140:141], v[2:3], 2, s[64:65]
	global_load_dword v125, v[140:141], off
	s_waitcnt vmcnt(7)
	v_mul_f32_e32 v23, 0xbfb8aa3b, v118
	v_exp_f32_e32 v23, v23
	s_nop 0
	v_add_f32_e32 v23, 1.0, v23
	v_rcp_f32_e32 v25, v23
	s_nop 0
	v_mul_f32_e32 v118, v118, v25
	ds_write_b32 v21, v118
	s_waitcnt vmcnt(6)
	v_mul_f32_e32 v23, 0xbfb8aa3b, v119
	v_exp_f32_e32 v23, v23
	s_nop 0
	v_add_f32_e32 v23, 1.0, v23
	v_rcp_f32_e32 v25, v23
	s_nop 0
	v_mul_f32_e32 v119, v119, v25
	ds_write_b32 v21, v119 offset:1024
	s_waitcnt vmcnt(5)
	v_mul_f32_e32 v23, 0xbfb8aa3b, v120
	v_exp_f32_e32 v23, v23
	s_nop 0
	v_add_f32_e32 v23, 1.0, v23
	v_rcp_f32_e32 v25, v23
	s_nop 0
	v_mul_f32_e32 v120, v120, v25
	ds_write_b32 v21, v120 offset:2048
	s_waitcnt vmcnt(4)
	v_mul_f32_e32 v23, 0xbfb8aa3b, v121
	v_exp_f32_e32 v23, v23
	s_nop 0
	v_add_f32_e32 v23, 1.0, v23
	v_rcp_f32_e32 v25, v23
	s_nop 0
	v_mul_f32_e32 v121, v121, v25
	ds_write_b32 v21, v121 offset:3072
	s_waitcnt vmcnt(3)
	v_mul_f32_e32 v23, 0xbfb8aa3b, v122
	v_exp_f32_e32 v23, v23
	s_nop 0
	v_add_f32_e32 v23, 1.0, v23
	v_rcp_f32_e32 v25, v23
	s_nop 0
	v_mul_f32_e32 v122, v122, v25
	ds_write_b32 v21, v122 offset:4096
	s_waitcnt vmcnt(2)
	v_mul_f32_e32 v23, 0xbfb8aa3b, v123
	v_exp_f32_e32 v23, v23
	s_nop 0
	v_add_f32_e32 v23, 1.0, v23
	v_rcp_f32_e32 v25, v23
	s_nop 0
	v_mul_f32_e32 v123, v123, v25
	ds_write_b32 v21, v123 offset:5120
	s_waitcnt vmcnt(1)
	v_mul_f32_e32 v23, 0xbfb8aa3b, v124
	v_exp_f32_e32 v23, v23
	s_nop 0
	v_add_f32_e32 v23, 1.0, v23
	v_rcp_f32_e32 v25, v23
	s_nop 0
	v_mul_f32_e32 v124, v124, v25
	ds_write_b32 v21, v124 offset:6144
	s_waitcnt vmcnt(0)
	v_mul_f32_e32 v23, 0xbfb8aa3b, v125
	v_exp_f32_e32 v23, v23
	s_nop 0
	v_add_f32_e32 v23, 1.0, v23
	v_rcp_f32_e32 v25, v23
	s_nop 0
	v_mul_f32_e32 v125, v125, v25
	ds_write_b32 v21, v125 offset:7168
	v_add_u32_e32 v2, 0xa00, v19
	v_and_b32_e32 v2, 0x3fff, v2
	v_add_u32_e32 v2, 0xfffffc00, v2
	v_lshl_add_u64 v[126:127], v[2:3], 2, s[64:65]
	global_load_dword v118, v[126:127], off
	v_add_u32_e32 v2, 0xb00, v19
	v_and_b32_e32 v2, 0x3fff, v2
	v_add_u32_e32 v2, 0xfffffc00, v2
	v_lshl_add_u64 v[128:129], v[2:3], 2, s[64:65]
	global_load_dword v119, v[128:129], off
	v_add_u32_e32 v2, 0xc00, v19
	v_and_b32_e32 v2, 0x3fff, v2
	v_add_u32_e32 v2, 0xfffffc00, v2
	v_lshl_add_u64 v[130:131], v[2:3], 2, s[64:65]
	global_load_dword v120, v[130:131], off
	v_add_u32_e32 v2, 0xd00, v19
	v_and_b32_e32 v2, 0x3fff, v2
	v_add_u32_e32 v2, 0xfffffc00, v2
	v_lshl_add_u64 v[132:133], v[2:3], 2, s[64:65]
	global_load_dword v121, v[132:133], off
	v_add_u32_e32 v2, 0xe00, v19
	v_and_b32_e32 v2, 0x3fff, v2
	v_add_u32_e32 v2, 0xfffffc00, v2
	v_lshl_add_u64 v[134:135], v[2:3], 2, s[64:65]
	global_load_dword v122, v[134:135], off
	v_add_u32_e32 v2, 0xf00, v19
	v_and_b32_e32 v2, 0x3fff, v2
	v_add_u32_e32 v2, 0xfffffc00, v2
	v_lshl_add_u64 v[136:137], v[2:3], 2, s[64:65]
	global_load_dword v123, v[136:137], off
	v_add_u32_e32 v2, 0x1000, v19
	v_and_b32_e32 v2, 0x3fff, v2
	v_add_u32_e32 v2, 0xfffffc00, v2
	v_lshl_add_u64 v[138:139], v[2:3], 2, s[64:65]
	global_load_dword v124, v[138:139], off
	v_add_u32_e32 v2, 0x1100, v19
	v_and_b32_e32 v2, 0x3fff, v2
	v_add_u32_e32 v2, 0xfffffc00, v2
	v_lshl_add_u64 v[140:141], v[2:3], 2, s[64:65]
	global_load_dword v125, v[140:141], off
	s_waitcnt vmcnt(7)
	v_mul_f32_e32 v23, 0xbfb8aa3b, v118
	v_exp_f32_e32 v23, v23
	s_nop 0
	v_add_f32_e32 v23, 1.0, v23
	v_rcp_f32_e32 v25, v23
	s_nop 0
	v_mul_f32_e32 v118, v118, v25
	ds_write_b32 v21, v118 offset:8192
	s_waitcnt vmcnt(6)
	v_mul_f32_e32 v23, 0xbfb8aa3b, v119
	v_exp_f32_e32 v23, v23
	s_nop 0
	v_add_f32_e32 v23, 1.0, v23
	v_rcp_f32_e32 v25, v23
	s_nop 0
	v_mul_f32_e32 v119, v119, v25
	ds_write_b32 v21, v119 offset:9216
	s_waitcnt vmcnt(5)
	v_mul_f32_e32 v23, 0xbfb8aa3b, v120
	v_exp_f32_e32 v23, v23
	s_nop 0
	v_add_f32_e32 v23, 1.0, v23
	v_rcp_f32_e32 v25, v23
	s_nop 0
	v_mul_f32_e32 v120, v120, v25
	ds_write_b32 v21, v120 offset:10240
	s_waitcnt vmcnt(4)
	v_mul_f32_e32 v23, 0xbfb8aa3b, v121
	v_exp_f32_e32 v23, v23
	s_nop 0
	v_add_f32_e32 v23, 1.0, v23
	v_rcp_f32_e32 v25, v23
	s_nop 0
	v_mul_f32_e32 v121, v121, v25
	ds_write_b32 v21, v121 offset:11264
	s_waitcnt vmcnt(3)
	v_mul_f32_e32 v23, 0xbfb8aa3b, v122
	v_exp_f32_e32 v23, v23
	s_nop 0
	v_add_f32_e32 v23, 1.0, v23
	v_rcp_f32_e32 v25, v23
	s_nop 0
	v_mul_f32_e32 v122, v122, v25
	ds_write_b32 v21, v122 offset:12288
	s_waitcnt vmcnt(2)
	v_mul_f32_e32 v23, 0xbfb8aa3b, v123
	v_exp_f32_e32 v23, v23
	s_nop 0
	v_add_f32_e32 v23, 1.0, v23
	v_rcp_f32_e32 v25, v23
	s_nop 0
	v_mul_f32_e32 v123, v123, v25
	ds_write_b32 v21, v123 offset:13312
	s_waitcnt vmcnt(1)
	v_mul_f32_e32 v23, 0xbfb8aa3b, v124
	v_exp_f32_e32 v23, v23
	s_nop 0
	v_add_f32_e32 v23, 1.0, v23
	v_rcp_f32_e32 v25, v23
	s_nop 0
	v_mul_f32_e32 v124, v124, v25
	ds_write_b32 v21, v124 offset:14336
	s_waitcnt vmcnt(0)
	v_mul_f32_e32 v23, 0xbfb8aa3b, v125
	v_exp_f32_e32 v23, v23
	s_nop 0
	v_add_f32_e32 v23, 1.0, v23
	v_rcp_f32_e32 v25, v23
	s_nop 0
	v_mul_f32_e32 v125, v125, v25
	ds_write_b32 v21, v125 offset:15360
	v_add_u32_e32 v2, 0x1200, v19
	v_and_b32_e32 v2, 0x3fff, v2
	v_add_u32_e32 v2, 0xfffffc00, v2
	v_lshl_add_u64 v[126:127], v[2:3], 2, s[64:65]
	global_load_dword v118, v[126:127], off
	v_add_u32_e32 v2, 0x1300, v19
	v_and_b32_e32 v2, 0x3fff, v2
	v_add_u32_e32 v2, 0xfffffc00, v2
	v_lshl_add_u64 v[128:129], v[2:3], 2, s[64:65]
	global_load_dword v119, v[128:129], off
	v_add_u32_e32 v2, 0x1400, v19
	v_and_b32_e32 v2, 0x3fff, v2
	v_add_u32_e32 v2, 0xfffffc00, v2
	v_lshl_add_u64 v[130:131], v[2:3], 2, s[64:65]
	global_load_dword v120, v[130:131], off
	v_add_u32_e32 v2, 0x1500, v19
	v_and_b32_e32 v2, 0x3fff, v2
	v_add_u32_e32 v2, 0xfffffc00, v2
	v_lshl_add_u64 v[132:133], v[2:3], 2, s[64:65]
	global_load_dword v121, v[132:133], off
	v_add_u32_e32 v2, 0x1600, v19
	v_and_b32_e32 v2, 0x3fff, v2
	v_add_u32_e32 v2, 0xfffffc00, v2
	v_lshl_add_u64 v[134:135], v[2:3], 2, s[64:65]
	global_load_dword v122, v[134:135], off
	v_add_u32_e32 v2, 0x1700, v19
	v_and_b32_e32 v2, 0x3fff, v2
	v_add_u32_e32 v2, 0xfffffc00, v2
	v_lshl_add_u64 v[136:137], v[2:3], 2, s[64:65]
	global_load_dword v123, v[136:137], off
	v_add_u32_e32 v2, 0x1800, v19
	v_and_b32_e32 v2, 0x3fff, v2
	v_add_u32_e32 v2, 0xfffffc00, v2
	v_lshl_add_u64 v[138:139], v[2:3], 2, s[64:65]
	global_load_dword v124, v[138:139], off
	v_add_u32_e32 v2, 0x1900, v19
	v_and_b32_e32 v2, 0x3fff, v2
	v_add_u32_e32 v2, 0xfffffc00, v2
	v_lshl_add_u64 v[140:141], v[2:3], 2, s[64:65]
	global_load_dword v125, v[140:141], off
	s_waitcnt vmcnt(7)
	v_mul_f32_e32 v23, 0xbfb8aa3b, v118
	v_exp_f32_e32 v23, v23
	s_nop 0
	v_add_f32_e32 v23, 1.0, v23
	v_rcp_f32_e32 v25, v23
	s_nop 0
	v_mul_f32_e32 v118, v118, v25
	ds_write_b32 v21, v118 offset:16384
	s_waitcnt vmcnt(6)
	v_mul_f32_e32 v23, 0xbfb8aa3b, v119
	v_exp_f32_e32 v23, v23
	s_nop 0
	v_add_f32_e32 v23, 1.0, v23
	v_rcp_f32_e32 v25, v23
	s_nop 0
	v_mul_f32_e32 v119, v119, v25
	ds_write_b32 v21, v119 offset:17408
	s_waitcnt vmcnt(5)
	v_mul_f32_e32 v23, 0xbfb8aa3b, v120
	v_exp_f32_e32 v23, v23
	s_nop 0
	v_add_f32_e32 v23, 1.0, v23
	v_rcp_f32_e32 v25, v23
	s_nop 0
	v_mul_f32_e32 v120, v120, v25
	ds_write_b32 v21, v120 offset:18432
	s_waitcnt vmcnt(4)
	v_mul_f32_e32 v23, 0xbfb8aa3b, v121
	v_exp_f32_e32 v23, v23
	s_nop 0
	v_add_f32_e32 v23, 1.0, v23
	v_rcp_f32_e32 v25, v23
	s_nop 0
	v_mul_f32_e32 v121, v121, v25
	ds_write_b32 v21, v121 offset:19456
	s_waitcnt vmcnt(3)
	v_mul_f32_e32 v23, 0xbfb8aa3b, v122
	v_exp_f32_e32 v23, v23
	s_nop 0
	v_add_f32_e32 v23, 1.0, v23
	v_rcp_f32_e32 v25, v23
	s_nop 0
	v_mul_f32_e32 v122, v122, v25
	ds_write_b32 v21, v122 offset:20480
	s_waitcnt vmcnt(2)
	v_mul_f32_e32 v23, 0xbfb8aa3b, v123
	v_exp_f32_e32 v23, v23
	s_nop 0
	v_add_f32_e32 v23, 1.0, v23
	v_rcp_f32_e32 v25, v23
	s_nop 0
	v_mul_f32_e32 v123, v123, v25
	ds_write_b32 v21, v123 offset:21504
	s_waitcnt vmcnt(1)
	v_mul_f32_e32 v23, 0xbfb8aa3b, v124
	v_exp_f32_e32 v23, v23
	s_nop 0
	v_add_f32_e32 v23, 1.0, v23
	v_rcp_f32_e32 v25, v23
	s_nop 0
	v_mul_f32_e32 v124, v124, v25
	ds_write_b32 v21, v124 offset:22528
	s_waitcnt vmcnt(0)
	v_mul_f32_e32 v23, 0xbfb8aa3b, v125
	v_exp_f32_e32 v23, v23
	s_nop 0
	v_add_f32_e32 v23, 1.0, v23
	v_rcp_f32_e32 v25, v23
	s_nop 0
	v_mul_f32_e32 v125, v125, v25
	ds_write_b32 v21, v125 offset:23552
	v_add_u32_e32 v2, 0x1a00, v19
	v_and_b32_e32 v2, 0x3fff, v2
	v_add_u32_e32 v2, 0xfffffc00, v2
	v_lshl_add_u64 v[126:127], v[2:3], 2, s[64:65]
	global_load_dword v118, v[126:127], off
	v_add_u32_e32 v2, 0x1b00, v19
	v_and_b32_e32 v2, 0x3fff, v2
	v_add_u32_e32 v2, 0xfffffc00, v2
	v_lshl_add_u64 v[128:129], v[2:3], 2, s[64:65]
	global_load_dword v119, v[128:129], off
	v_add_u32_e32 v2, 0x1c00, v19
	v_and_b32_e32 v2, 0x3fff, v2
	v_add_u32_e32 v2, 0xfffffc00, v2
	v_lshl_add_u64 v[130:131], v[2:3], 2, s[64:65]
	global_load_dword v120, v[130:131], off
	v_add_u32_e32 v2, 0x1d00, v19
	v_and_b32_e32 v2, 0x3fff, v2
	v_add_u32_e32 v2, 0xfffffc00, v2
	v_lshl_add_u64 v[132:133], v[2:3], 2, s[64:65]
	global_load_dword v121, v[132:133], off
	v_add_u32_e32 v2, 0x1e00, v19
	v_and_b32_e32 v2, 0x3fff, v2
	v_add_u32_e32 v2, 0xfffffc00, v2
	v_lshl_add_u64 v[134:135], v[2:3], 2, s[64:65]
	global_load_dword v122, v[134:135], off
	v_add_u32_e32 v2, 0x1f00, v19
	v_and_b32_e32 v2, 0x3fff, v2
	v_add_u32_e32 v2, 0xfffffc00, v2
	v_lshl_add_u64 v[136:137], v[2:3], 2, s[64:65]
	global_load_dword v123, v[136:137], off
	v_add_u32_e32 v2, 0x2000, v19
	v_and_b32_e32 v2, 0x3fff, v2
	v_add_u32_e32 v2, 0xfffffc00, v2
	v_lshl_add_u64 v[138:139], v[2:3], 2, s[64:65]
	global_load_dword v124, v[138:139], off
	v_add_u32_e32 v2, 0x2100, v19
	v_and_b32_e32 v2, 0x3fff, v2
	v_add_u32_e32 v2, 0xfffffc00, v2
	v_lshl_add_u64 v[140:141], v[2:3], 2, s[64:65]
	global_load_dword v125, v[140:141], off
	s_waitcnt vmcnt(7)
	v_mul_f32_e32 v23, 0xbfb8aa3b, v118
	v_exp_f32_e32 v23, v23
	s_nop 0
	v_add_f32_e32 v23, 1.0, v23
	v_rcp_f32_e32 v25, v23
	s_nop 0
	v_mul_f32_e32 v118, v118, v25
	ds_write_b32 v21, v118 offset:24576
	s_waitcnt vmcnt(6)
	v_mul_f32_e32 v23, 0xbfb8aa3b, v119
	v_exp_f32_e32 v23, v23
	s_nop 0
	v_add_f32_e32 v23, 1.0, v23
	v_rcp_f32_e32 v25, v23
	s_nop 0
	v_mul_f32_e32 v119, v119, v25
	ds_write_b32 v21, v119 offset:25600
	s_waitcnt vmcnt(5)
	v_mul_f32_e32 v23, 0xbfb8aa3b, v120
	v_exp_f32_e32 v23, v23
	s_nop 0
	v_add_f32_e32 v23, 1.0, v23
	v_rcp_f32_e32 v25, v23
	s_nop 0
	v_mul_f32_e32 v120, v120, v25
	ds_write_b32 v21, v120 offset:26624
	s_waitcnt vmcnt(4)
	v_mul_f32_e32 v23, 0xbfb8aa3b, v121
	v_exp_f32_e32 v23, v23
	s_nop 0
	v_add_f32_e32 v23, 1.0, v23
	v_rcp_f32_e32 v25, v23
	s_nop 0
	v_mul_f32_e32 v121, v121, v25
	ds_write_b32 v21, v121 offset:27648
	s_waitcnt vmcnt(3)
	v_mul_f32_e32 v23, 0xbfb8aa3b, v122
	v_exp_f32_e32 v23, v23
	s_nop 0
	v_add_f32_e32 v23, 1.0, v23
	v_rcp_f32_e32 v25, v23
	s_nop 0
	v_mul_f32_e32 v122, v122, v25
	ds_write_b32 v21, v122 offset:28672
	s_waitcnt vmcnt(2)
	v_mul_f32_e32 v23, 0xbfb8aa3b, v123
	v_exp_f32_e32 v23, v23
	s_nop 0
	v_add_f32_e32 v23, 1.0, v23
	v_rcp_f32_e32 v25, v23
	s_nop 0
	v_mul_f32_e32 v123, v123, v25
	ds_write_b32 v21, v123 offset:29696
	s_waitcnt vmcnt(1)
	v_mul_f32_e32 v23, 0xbfb8aa3b, v124
	v_exp_f32_e32 v23, v23
	s_nop 0
	v_add_f32_e32 v23, 1.0, v23
	v_rcp_f32_e32 v25, v23
	s_nop 0
	v_mul_f32_e32 v124, v124, v25
	ds_write_b32 v21, v124 offset:30720
	s_waitcnt vmcnt(0)
	v_mul_f32_e32 v23, 0xbfb8aa3b, v125
	v_exp_f32_e32 v23, v23
	s_nop 0
	v_add_f32_e32 v23, 1.0, v23
	v_rcp_f32_e32 v25, v23
	s_nop 0
	v_mul_f32_e32 v125, v125, v25
	ds_write_b32 v21, v125 offset:31744
	s_or_b64 exec, exec, s[30:31]
	v_mul_hi_i32 v2, v1, s43
	v_lshrrev_b32_e32 v19, 31, v2
	v_ashrrev_i32_e32 v2, 3, v2
	v_add_u32_e32 v2, v2, v19
	v_mul_lo_u32 v19, v2, 48
	v_sub_u32_e32 v19, v1, v19
	v_lshlrev_b32_e32 v38, 6, v19
	v_ashrrev_i32_e32 v39, 31, v38
	v_lshlrev_b64 v[36:37], 2, v[38:39]
	v_mad_i64_i32 v[40:41], s[2:3], v2, s44, v[36:37]
	v_mov_b32_e32 v42, 0
	v_lshl_add_u64 v[40:41], v[14:15], 0, v[40:41]
	s_mov_b64 s[2:3], 0
	v_mov_b32_e32 v19, v57
	v_mov_b32_e32 v43, v42
	v_mov_b32_e32 v44, v42
	v_mov_b32_e32 v45, v42
	v_mov_b32_e32 v46, v42
	v_mov_b32_e32 v47, v42
	v_mov_b32_e32 v48, v42
	v_mov_b32_e32 v49, v42
	v_mov_b32_e32 v21, v42
	s_waitcnt lgkmcnt(0)
	s_barrier
	v_mov_b32_e32 v150, v40
	v_mov_b32_e32 v151, v41
	v_add_co_u32_e32 v152, vcc, 0x3000, v40
	s_nop 1
	v_addc_co_u32_e32 v153, vcc, 0, v41, vcc
	v_add_co_u32_e32 v154, vcc, 0x6000, v40
	s_nop 1
	v_addc_co_u32_e32 v155, vcc, 0, v41, vcc
	v_add_co_u32_e32 v156, vcc, 0x9000, v40
	s_nop 1
	v_addc_co_u32_e32 v157, vcc, 0, v41, vcc
	s_mov_b64 s[2:3], 0xc000
	s_nop 0
	global_load_dword v118, v[150:151], off
	global_load_dword v119, v[152:153], off
	global_load_dword v120, v[154:155], off
	global_load_dword v121, v[156:157], off
	v_lshl_add_u64 v[150:151], v[150:151], 0, s[2:3]
	v_lshl_add_u64 v[152:153], v[152:153], 0, s[2:3]
	v_lshl_add_u64 v[154:155], v[154:155], 0, s[2:3]
	v_lshl_add_u64 v[156:157], v[156:157], 0, s[2:3]
	global_load_dword v122, v[150:151], off
	global_load_dword v123, v[152:153], off
	global_load_dword v124, v[154:155], off
	global_load_dword v125, v[156:157], off
	v_lshl_add_u64 v[150:151], v[150:151], 0, s[2:3]
	v_lshl_add_u64 v[152:153], v[152:153], 0, s[2:3]
	v_lshl_add_u64 v[154:155], v[154:155], 0, s[2:3]
	v_lshl_add_u64 v[156:157], v[156:157], 0, s[2:3]
	global_load_dword v126, v[150:151], off
	global_load_dword v127, v[152:153], off
	global_load_dword v128, v[154:155], off
	global_load_dword v129, v[156:157], off
	v_lshl_add_u64 v[150:151], v[150:151], 0, s[2:3]
	v_lshl_add_u64 v[152:153], v[152:153], 0, s[2:3]
	v_lshl_add_u64 v[154:155], v[154:155], 0, s[2:3]
	v_lshl_add_u64 v[156:157], v[156:157], 0, s[2:3]
	global_load_dword v130, v[150:151], off
	global_load_dword v131, v[152:153], off
	global_load_dword v132, v[154:155], off
	global_load_dword v133, v[156:157], off
	v_lshl_add_u64 v[150:151], v[150:151], 0, s[2:3]
	v_lshl_add_u64 v[152:153], v[152:153], 0, s[2:3]
	v_lshl_add_u64 v[154:155], v[154:155], 0, s[2:3]
	v_lshl_add_u64 v[156:157], v[156:157], 0, s[2:3]
	global_load_dword v134, v[150:151], off
	global_load_dword v135, v[152:153], off
	global_load_dword v136, v[154:155], off
	global_load_dword v137, v[156:157], off
	v_lshl_add_u64 v[150:151], v[150:151], 0, s[2:3]
	v_lshl_add_u64 v[152:153], v[152:153], 0, s[2:3]
	v_lshl_add_u64 v[154:155], v[154:155], 0, s[2:3]
	v_lshl_add_u64 v[156:157], v[156:157], 0, s[2:3]
	global_load_dword v138, v[150:151], off
	global_load_dword v139, v[152:153], off
	global_load_dword v140, v[154:155], off
	global_load_dword v141, v[156:157], off
	v_lshl_add_u64 v[150:151], v[150:151], 0, s[2:3]
	v_lshl_add_u64 v[152:153], v[152:153], 0, s[2:3]
	v_lshl_add_u64 v[154:155], v[154:155], 0, s[2:3]
	v_lshl_add_u64 v[156:157], v[156:157], 0, s[2:3]
	global_load_dword v142, v[150:151], off
	global_load_dword v143, v[152:153], off
	global_load_dword v144, v[154:155], off
	global_load_dword v145, v[156:157], off
	v_lshl_add_u64 v[150:151], v[150:151], 0, s[2:3]
	v_lshl_add_u64 v[152:153], v[152:153], 0, s[2:3]
	v_lshl_add_u64 v[154:155], v[154:155], 0, s[2:3]
	v_lshl_add_u64 v[156:157], v[156:157], 0, s[2:3]
	global_load_dword v146, v[150:151], off
	global_load_dword v147, v[152:153], off
	global_load_dword v148, v[154:155], off
	global_load_dword v149, v[156:157], off
	v_lshl_add_u64 v[150:151], v[150:151], 0, s[2:3]
	v_lshl_add_u64 v[152:153], v[152:153], 0, s[2:3]
	v_lshl_add_u64 v[154:155], v[154:155], 0, s[2:3]
	v_lshl_add_u64 v[156:157], v[156:157], 0, s[2:3]
	s_mov_b32 vcc_lo, 7
.Lmod_k:
	ds_read_b128 v[66:69], v19 offset:4096
	ds_read_b128 v[70:73], v19 offset:8192
	ds_read_b128 v[74:77], v19 offset:12288
	ds_read_b128 v[78:81], v19 offset:16384
	ds_read_b128 v[82:85], v19 offset:20480
	ds_read_b128 v[86:89], v19 offset:24576
	ds_read_b128 v[90:93], v19 offset:28672
	ds_read_b128 v[94:97], v19
	ds_read_b128 v[98:101], v19 offset:32768
	s_waitcnt lgkmcnt(8)
	v_mov_b32_e32 v111, v66
	s_waitcnt lgkmcnt(7)
	v_mov_b32_e32 v112, v70
	s_waitcnt lgkmcnt(6)
	v_mov_b32_e32 v113, v74
	s_waitcnt lgkmcnt(1)
	v_mov_b32_e32 v110, v94
	v_mov_b32_e32 v114, v78
	v_mov_b32_e32 v115, v82
	v_mov_b32_e32 v116, v86
	v_mov_b32_e32 v117, v90
	v_mov_b32_e32 v66, v95
	v_mov_b32_e32 v74, v71
	v_mov_b32_e32 v82, v79
	v_mov_b32_e32 v90, v87
	v_mov_b32_e32 v70, v96
	v_mov_b32_e32 v71, v68
	v_mov_b32_e32 v78, v72
	v_mov_b32_e32 v79, v76
	v_mov_b32_e32 v86, v80
	v_mov_b32_e32 v87, v84
	v_mov_b32_e32 v94, v88
	v_mov_b32_e32 v95, v92
	v_mov_b32_e32 v68, v97
	v_mov_b32_e32 v76, v73
	v_mov_b32_e32 v84, v81
	v_mov_b32_e32 v92, v89
	v_add_u32_e32 v19, 16, v19
	s_waitcnt vmcnt(31)
	v_pk_fma_f32 v[42:43], v[118:119], v[110:111], v[42:43] op_sel_hi:[0,1,1]
	v_pk_fma_f32 v[44:45], v[118:119], v[112:113], v[44:45] op_sel_hi:[0,1,1]
	v_pk_fma_f32 v[46:47], v[118:119], v[114:115], v[46:47] op_sel_hi:[0,1,1]
	v_pk_fma_f32 v[48:49], v[118:119], v[116:117], v[48:49] op_sel_hi:[0,1,1]
	s_waitcnt lgkmcnt(0)
	v_fmac_f32_e32 v21, v118, v98
	s_waitcnt vmcnt(30)
	v_pk_fma_f32 v[42:43], v[118:119], v[66:67], v[42:43] op_sel:[1,0,0] op_sel_hi:[1,1,1]
	v_pk_fma_f32 v[44:45], v[118:119], v[74:75], v[44:45] op_sel:[1,0,0] op_sel_hi:[1,1,1]
	v_pk_fma_f32 v[46:47], v[118:119], v[82:83], v[46:47] op_sel:[1,0,0] op_sel_hi:[1,1,1]
	v_pk_fma_f32 v[48:49], v[118:119], v[90:91], v[48:49] op_sel:[1,0,0] op_sel_hi:[1,1,1]
	v_fmac_f32_e32 v21, v119, v99
	s_waitcnt vmcnt(29)
	v_pk_fma_f32 v[42:43], v[120:121], v[70:71], v[42:43] op_sel_hi:[0,1,1]
	v_pk_fma_f32 v[44:45], v[120:121], v[78:79], v[44:45] op_sel_hi:[0,1,1]
	v_pk_fma_f32 v[46:47], v[120:121], v[86:87], v[46:47] op_sel_hi:[0,1,1]
	v_pk_fma_f32 v[48:49], v[120:121], v[94:95], v[48:49] op_sel_hi:[0,1,1]
	v_fmac_f32_e32 v21, v120, v100
	s_waitcnt vmcnt(28)
	v_pk_fma_f32 v[42:43], v[120:121], v[68:69], v[42:43] op_sel:[1,0,0] op_sel_hi:[1,1,1]
	v_pk_fma_f32 v[44:45], v[120:121], v[76:77], v[44:45] op_sel:[1,0,0] op_sel_hi:[1,1,1]
	v_pk_fma_f32 v[46:47], v[120:121], v[84:85], v[46:47] op_sel:[1,0,0] op_sel_hi:[1,1,1]
	v_pk_fma_f32 v[48:49], v[120:121], v[92:93], v[48:49] op_sel:[1,0,0] op_sel_hi:[1,1,1]
	v_fmac_f32_e32 v21, v121, v101
	global_load_dword v118, v[150:151], off
	global_load_dword v119, v[152:153], off
	global_load_dword v120, v[154:155], off
	global_load_dword v121, v[156:157], off
	v_lshl_add_u64 v[150:151], v[150:151], 0, s[2:3]
	v_lshl_add_u64 v[152:153], v[152:153], 0, s[2:3]
	v_lshl_add_u64 v[154:155], v[154:155], 0, s[2:3]
	v_lshl_add_u64 v[156:157], v[156:157], 0, s[2:3]
	ds_read_b128 v[66:69], v19 offset:4096
	ds_read_b128 v[70:73], v19 offset:8192
	ds_read_b128 v[74:77], v19 offset:12288
	ds_read_b128 v[78:81], v19 offset:16384
	ds_read_b128 v[82:85], v19 offset:20480
	ds_read_b128 v[86:89], v19 offset:24576
	ds_read_b128 v[90:93], v19 offset:28672
	ds_read_b128 v[94:97], v19
	ds_read_b128 v[98:101], v19 offset:32768
	s_waitcnt lgkmcnt(8)
	v_mov_b32_e32 v111, v66
	s_waitcnt lgkmcnt(7)
	v_mov_b32_e32 v112, v70
	s_waitcnt lgkmcnt(6)
	v_mov_b32_e32 v113, v74
	s_waitcnt lgkmcnt(1)
	v_mov_b32_e32 v110, v94
	v_mov_b32_e32 v114, v78
	v_mov_b32_e32 v115, v82
	v_mov_b32_e32 v116, v86
	v_mov_b32_e32 v117, v90
	v_mov_b32_e32 v66, v95
	v_mov_b32_e32 v74, v71
	v_mov_b32_e32 v82, v79
	v_mov_b32_e32 v90, v87
	v_mov_b32_e32 v70, v96
	v_mov_b32_e32 v71, v68
	v_mov_b32_e32 v78, v72
	v_mov_b32_e32 v79, v76
	v_mov_b32_e32 v86, v80
	v_mov_b32_e32 v87, v84
	v_mov_b32_e32 v94, v88
	v_mov_b32_e32 v95, v92
	v_mov_b32_e32 v68, v97
	v_mov_b32_e32 v76, v73
	v_mov_b32_e32 v84, v81
	v_mov_b32_e32 v92, v89
	v_add_u32_e32 v19, 16, v19
	s_waitcnt vmcnt(31)
	v_pk_fma_f32 v[42:43], v[122:123], v[110:111], v[42:43] op_sel_hi:[0,1,1]
	v_pk_fma_f32 v[44:45], v[122:123], v[112:113], v[44:45] op_sel_hi:[0,1,1]
	v_pk_fma_f32 v[46:47], v[122:123], v[114:115], v[46:47] op_sel_hi:[0,1,1]
	v_pk_fma_f32 v[48:49], v[122:123], v[116:117], v[48:49] op_sel_hi:[0,1,1]
	s_waitcnt lgkmcnt(0)
	v_fmac_f32_e32 v21, v122, v98
	s_waitcnt vmcnt(30)
	v_pk_fma_f32 v[42:43], v[122:123], v[66:67], v[42:43] op_sel:[1,0,0] op_sel_hi:[1,1,1]
	v_pk_fma_f32 v[44:45], v[122:123], v[74:75], v[44:45] op_sel:[1,0,0] op_sel_hi:[1,1,1]
	v_pk_fma_f32 v[46:47], v[122:123], v[82:83], v[46:47] op_sel:[1,0,0] op_sel_hi:[1,1,1]
	v_pk_fma_f32 v[48:49], v[122:123], v[90:91], v[48:49] op_sel:[1,0,0] op_sel_hi:[1,1,1]
	v_fmac_f32_e32 v21, v123, v99
	s_waitcnt vmcnt(29)
	v_pk_fma_f32 v[42:43], v[124:125], v[70:71], v[42:43] op_sel_hi:[0,1,1]
	v_pk_fma_f32 v[44:45], v[124:125], v[78:79], v[44:45] op_sel_hi:[0,1,1]
	v_pk_fma_f32 v[46:47], v[124:125], v[86:87], v[46:47] op_sel_hi:[0,1,1]
	v_pk_fma_f32 v[48:49], v[124:125], v[94:95], v[48:49] op_sel_hi:[0,1,1]
	v_fmac_f32_e32 v21, v124, v100
	s_waitcnt vmcnt(28)
	v_pk_fma_f32 v[42:43], v[124:125], v[68:69], v[42:43] op_sel:[1,0,0] op_sel_hi:[1,1,1]
	v_pk_fma_f32 v[44:45], v[124:125], v[76:77], v[44:45] op_sel:[1,0,0] op_sel_hi:[1,1,1]
	v_pk_fma_f32 v[46:47], v[124:125], v[84:85], v[46:47] op_sel:[1,0,0] op_sel_hi:[1,1,1]
	v_pk_fma_f32 v[48:49], v[124:125], v[92:93], v[48:49] op_sel:[1,0,0] op_sel_hi:[1,1,1]
	v_fmac_f32_e32 v21, v125, v101
	global_load_dword v122, v[150:151], off
	global_load_dword v123, v[152:153], off
	global_load_dword v124, v[154:155], off
	global_load_dword v125, v[156:157], off
	v_lshl_add_u64 v[150:151], v[150:151], 0, s[2:3]
	v_lshl_add_u64 v[152:153], v[152:153], 0, s[2:3]
	v_lshl_add_u64 v[154:155], v[154:155], 0, s[2:3]
	v_lshl_add_u64 v[156:157], v[156:157], 0, s[2:3]
	ds_read_b128 v[66:69], v19 offset:4096
	ds_read_b128 v[70:73], v19 offset:8192
	ds_read_b128 v[74:77], v19 offset:12288
	ds_read_b128 v[78:81], v19 offset:16384
	ds_read_b128 v[82:85], v19 offset:20480
	ds_read_b128 v[86:89], v19 offset:24576
	ds_read_b128 v[90:93], v19 offset:28672
	ds_read_b128 v[94:97], v19
	ds_read_b128 v[98:101], v19 offset:32768
	s_waitcnt lgkmcnt(8)
	v_mov_b32_e32 v111, v66
	s_waitcnt lgkmcnt(7)
	v_mov_b32_e32 v112, v70
	s_waitcnt lgkmcnt(6)
	v_mov_b32_e32 v113, v74
	s_waitcnt lgkmcnt(1)
	v_mov_b32_e32 v110, v94
	v_mov_b32_e32 v114, v78
	v_mov_b32_e32 v115, v82
	v_mov_b32_e32 v116, v86
	v_mov_b32_e32 v117, v90
	v_mov_b32_e32 v66, v95
	v_mov_b32_e32 v74, v71
	v_mov_b32_e32 v82, v79
	v_mov_b32_e32 v90, v87
	v_mov_b32_e32 v70, v96
	v_mov_b32_e32 v71, v68
	v_mov_b32_e32 v78, v72
	v_mov_b32_e32 v79, v76
	v_mov_b32_e32 v86, v80
	v_mov_b32_e32 v87, v84
	v_mov_b32_e32 v94, v88
	v_mov_b32_e32 v95, v92
	v_mov_b32_e32 v68, v97
	v_mov_b32_e32 v76, v73
	v_mov_b32_e32 v84, v81
	v_mov_b32_e32 v92, v89
	v_add_u32_e32 v19, 16, v19
	s_waitcnt vmcnt(31)
	v_pk_fma_f32 v[42:43], v[126:127], v[110:111], v[42:43] op_sel_hi:[0,1,1]
	v_pk_fma_f32 v[44:45], v[126:127], v[112:113], v[44:45] op_sel_hi:[0,1,1]
	v_pk_fma_f32 v[46:47], v[126:127], v[114:115], v[46:47] op_sel_hi:[0,1,1]
	v_pk_fma_f32 v[48:49], v[126:127], v[116:117], v[48:49] op_sel_hi:[0,1,1]
	s_waitcnt lgkmcnt(0)
	v_fmac_f32_e32 v21, v126, v98
	s_waitcnt vmcnt(30)
	v_pk_fma_f32 v[42:43], v[126:127], v[66:67], v[42:43] op_sel:[1,0,0] op_sel_hi:[1,1,1]
	v_pk_fma_f32 v[44:45], v[126:127], v[74:75], v[44:45] op_sel:[1,0,0] op_sel_hi:[1,1,1]
	v_pk_fma_f32 v[46:47], v[126:127], v[82:83], v[46:47] op_sel:[1,0,0] op_sel_hi:[1,1,1]
	v_pk_fma_f32 v[48:49], v[126:127], v[90:91], v[48:49] op_sel:[1,0,0] op_sel_hi:[1,1,1]
	v_fmac_f32_e32 v21, v127, v99
	s_waitcnt vmcnt(29)
	v_pk_fma_f32 v[42:43], v[128:129], v[70:71], v[42:43] op_sel_hi:[0,1,1]
	v_pk_fma_f32 v[44:45], v[128:129], v[78:79], v[44:45] op_sel_hi:[0,1,1]
	v_pk_fma_f32 v[46:47], v[128:129], v[86:87], v[46:47] op_sel_hi:[0,1,1]
	v_pk_fma_f32 v[48:49], v[128:129], v[94:95], v[48:49] op_sel_hi:[0,1,1]
	v_fmac_f32_e32 v21, v128, v100
	s_waitcnt vmcnt(28)
	v_pk_fma_f32 v[42:43], v[128:129], v[68:69], v[42:43] op_sel:[1,0,0] op_sel_hi:[1,1,1]
	v_pk_fma_f32 v[44:45], v[128:129], v[76:77], v[44:45] op_sel:[1,0,0] op_sel_hi:[1,1,1]
	v_pk_fma_f32 v[46:47], v[128:129], v[84:85], v[46:47] op_sel:[1,0,0] op_sel_hi:[1,1,1]
	v_pk_fma_f32 v[48:49], v[128:129], v[92:93], v[48:49] op_sel:[1,0,0] op_sel_hi:[1,1,1]
	v_fmac_f32_e32 v21, v129, v101
	global_load_dword v126, v[150:151], off
	global_load_dword v127, v[152:153], off
	global_load_dword v128, v[154:155], off
	global_load_dword v129, v[156:157], off
	v_lshl_add_u64 v[150:151], v[150:151], 0, s[2:3]
	v_lshl_add_u64 v[152:153], v[152:153], 0, s[2:3]
	v_lshl_add_u64 v[154:155], v[154:155], 0, s[2:3]
	v_lshl_add_u64 v[156:157], v[156:157], 0, s[2:3]
	ds_read_b128 v[66:69], v19 offset:4096
	ds_read_b128 v[70:73], v19 offset:8192
	ds_read_b128 v[74:77], v19 offset:12288
	ds_read_b128 v[78:81], v19 offset:16384
	ds_read_b128 v[82:85], v19 offset:20480
	ds_read_b128 v[86:89], v19 offset:24576
	ds_read_b128 v[90:93], v19 offset:28672
	ds_read_b128 v[94:97], v19
	ds_read_b128 v[98:101], v19 offset:32768
	s_waitcnt lgkmcnt(8)
	v_mov_b32_e32 v111, v66
	s_waitcnt lgkmcnt(7)
	v_mov_b32_e32 v112, v70
	s_waitcnt lgkmcnt(6)
	v_mov_b32_e32 v113, v74
	s_waitcnt lgkmcnt(1)
	v_mov_b32_e32 v110, v94
	v_mov_b32_e32 v114, v78
	v_mov_b32_e32 v115, v82
	v_mov_b32_e32 v116, v86
	v_mov_b32_e32 v117, v90
	v_mov_b32_e32 v66, v95
	v_mov_b32_e32 v74, v71
	v_mov_b32_e32 v82, v79
	v_mov_b32_e32 v90, v87
	v_mov_b32_e32 v70, v96
	v_mov_b32_e32 v71, v68
	v_mov_b32_e32 v78, v72
	v_mov_b32_e32 v79, v76
	v_mov_b32_e32 v86, v80
	v_mov_b32_e32 v87, v84
	v_mov_b32_e32 v94, v88
	v_mov_b32_e32 v95, v92
	v_mov_b32_e32 v68, v97
	v_mov_b32_e32 v76, v73
	v_mov_b32_e32 v84, v81
	v_mov_b32_e32 v92, v89
	v_add_u32_e32 v19, 16, v19
	s_waitcnt vmcnt(31)
	v_pk_fma_f32 v[42:43], v[130:131], v[110:111], v[42:43] op_sel_hi:[0,1,1]
	v_pk_fma_f32 v[44:45], v[130:131], v[112:113], v[44:45] op_sel_hi:[0,1,1]
	v_pk_fma_f32 v[46:47], v[130:131], v[114:115], v[46:47] op_sel_hi:[0,1,1]
	v_pk_fma_f32 v[48:49], v[130:131], v[116:117], v[48:49] op_sel_hi:[0,1,1]
	s_waitcnt lgkmcnt(0)
	v_fmac_f32_e32 v21, v130, v98
	s_waitcnt vmcnt(30)
	v_pk_fma_f32 v[42:43], v[130:131], v[66:67], v[42:43] op_sel:[1,0,0] op_sel_hi:[1,1,1]
	v_pk_fma_f32 v[44:45], v[130:131], v[74:75], v[44:45] op_sel:[1,0,0] op_sel_hi:[1,1,1]
	v_pk_fma_f32 v[46:47], v[130:131], v[82:83], v[46:47] op_sel:[1,0,0] op_sel_hi:[1,1,1]
	v_pk_fma_f32 v[48:49], v[130:131], v[90:91], v[48:49] op_sel:[1,0,0] op_sel_hi:[1,1,1]
	v_fmac_f32_e32 v21, v131, v99
	s_waitcnt vmcnt(29)
	v_pk_fma_f32 v[42:43], v[132:133], v[70:71], v[42:43] op_sel_hi:[0,1,1]
	v_pk_fma_f32 v[44:45], v[132:133], v[78:79], v[44:45] op_sel_hi:[0,1,1]
	v_pk_fma_f32 v[46:47], v[132:133], v[86:87], v[46:47] op_sel_hi:[0,1,1]
	v_pk_fma_f32 v[48:49], v[132:133], v[94:95], v[48:49] op_sel_hi:[0,1,1]
	v_fmac_f32_e32 v21, v132, v100
	s_waitcnt vmcnt(28)
	v_pk_fma_f32 v[42:43], v[132:133], v[68:69], v[42:43] op_sel:[1,0,0] op_sel_hi:[1,1,1]
	v_pk_fma_f32 v[44:45], v[132:133], v[76:77], v[44:45] op_sel:[1,0,0] op_sel_hi:[1,1,1]
	v_pk_fma_f32 v[46:47], v[132:133], v[84:85], v[46:47] op_sel:[1,0,0] op_sel_hi:[1,1,1]
	v_pk_fma_f32 v[48:49], v[132:133], v[92:93], v[48:49] op_sel:[1,0,0] op_sel_hi:[1,1,1]
	v_fmac_f32_e32 v21, v133, v101
	global_load_dword v130, v[150:151], off
	global_load_dword v131, v[152:153], off
	global_load_dword v132, v[154:155], off
	global_load_dword v133, v[156:157], off
	v_lshl_add_u64 v[150:151], v[150:151], 0, s[2:3]
	v_lshl_add_u64 v[152:153], v[152:153], 0, s[2:3]
	v_lshl_add_u64 v[154:155], v[154:155], 0, s[2:3]
	v_lshl_add_u64 v[156:157], v[156:157], 0, s[2:3]
	ds_read_b128 v[66:69], v19 offset:4096
	ds_read_b128 v[70:73], v19 offset:8192
	ds_read_b128 v[74:77], v19 offset:12288
	ds_read_b128 v[78:81], v19 offset:16384
	ds_read_b128 v[82:85], v19 offset:20480
	ds_read_b128 v[86:89], v19 offset:24576
	ds_read_b128 v[90:93], v19 offset:28672
	ds_read_b128 v[94:97], v19
	ds_read_b128 v[98:101], v19 offset:32768
	s_waitcnt lgkmcnt(8)
	v_mov_b32_e32 v111, v66
	s_waitcnt lgkmcnt(7)
	v_mov_b32_e32 v112, v70
	s_waitcnt lgkmcnt(6)
	v_mov_b32_e32 v113, v74
	s_waitcnt lgkmcnt(1)
	v_mov_b32_e32 v110, v94
	v_mov_b32_e32 v114, v78
	v_mov_b32_e32 v115, v82
	v_mov_b32_e32 v116, v86
	v_mov_b32_e32 v117, v90
	v_mov_b32_e32 v66, v95
	v_mov_b32_e32 v74, v71
	v_mov_b32_e32 v82, v79
	v_mov_b32_e32 v90, v87
	v_mov_b32_e32 v70, v96
	v_mov_b32_e32 v71, v68
	v_mov_b32_e32 v78, v72
	v_mov_b32_e32 v79, v76
	v_mov_b32_e32 v86, v80
	v_mov_b32_e32 v87, v84
	v_mov_b32_e32 v94, v88
	v_mov_b32_e32 v95, v92
	v_mov_b32_e32 v68, v97
	v_mov_b32_e32 v76, v73
	v_mov_b32_e32 v84, v81
	v_mov_b32_e32 v92, v89
	v_add_u32_e32 v19, 16, v19
	s_waitcnt vmcnt(31)
	v_pk_fma_f32 v[42:43], v[134:135], v[110:111], v[42:43] op_sel_hi:[0,1,1]
	v_pk_fma_f32 v[44:45], v[134:135], v[112:113], v[44:45] op_sel_hi:[0,1,1]
	v_pk_fma_f32 v[46:47], v[134:135], v[114:115], v[46:47] op_sel_hi:[0,1,1]
	v_pk_fma_f32 v[48:49], v[134:135], v[116:117], v[48:49] op_sel_hi:[0,1,1]
	s_waitcnt lgkmcnt(0)
	v_fmac_f32_e32 v21, v134, v98
	s_waitcnt vmcnt(30)
	v_pk_fma_f32 v[42:43], v[134:135], v[66:67], v[42:43] op_sel:[1,0,0] op_sel_hi:[1,1,1]
	v_pk_fma_f32 v[44:45], v[134:135], v[74:75], v[44:45] op_sel:[1,0,0] op_sel_hi:[1,1,1]
	v_pk_fma_f32 v[46:47], v[134:135], v[82:83], v[46:47] op_sel:[1,0,0] op_sel_hi:[1,1,1]
	v_pk_fma_f32 v[48:49], v[134:135], v[90:91], v[48:49] op_sel:[1,0,0] op_sel_hi:[1,1,1]
	v_fmac_f32_e32 v21, v135, v99
	s_waitcnt vmcnt(29)
	v_pk_fma_f32 v[42:43], v[136:137], v[70:71], v[42:43] op_sel_hi:[0,1,1]
	v_pk_fma_f32 v[44:45], v[136:137], v[78:79], v[44:45] op_sel_hi:[0,1,1]
	v_pk_fma_f32 v[46:47], v[136:137], v[86:87], v[46:47] op_sel_hi:[0,1,1]
	v_pk_fma_f32 v[48:49], v[136:137], v[94:95], v[48:49] op_sel_hi:[0,1,1]
	v_fmac_f32_e32 v21, v136, v100
	s_waitcnt vmcnt(28)
	v_pk_fma_f32 v[42:43], v[136:137], v[68:69], v[42:43] op_sel:[1,0,0] op_sel_hi:[1,1,1]
	v_pk_fma_f32 v[44:45], v[136:137], v[76:77], v[44:45] op_sel:[1,0,0] op_sel_hi:[1,1,1]
	v_pk_fma_f32 v[46:47], v[136:137], v[84:85], v[46:47] op_sel:[1,0,0] op_sel_hi:[1,1,1]
	v_pk_fma_f32 v[48:49], v[136:137], v[92:93], v[48:49] op_sel:[1,0,0] op_sel_hi:[1,1,1]
	v_fmac_f32_e32 v21, v137, v101
	global_load_dword v134, v[150:151], off
	global_load_dword v135, v[152:153], off
	global_load_dword v136, v[154:155], off
	global_load_dword v137, v[156:157], off
	v_lshl_add_u64 v[150:151], v[150:151], 0, s[2:3]
	v_lshl_add_u64 v[152:153], v[152:153], 0, s[2:3]
	v_lshl_add_u64 v[154:155], v[154:155], 0, s[2:3]
	v_lshl_add_u64 v[156:157], v[156:157], 0, s[2:3]
	ds_read_b128 v[66:69], v19 offset:4096
	ds_read_b128 v[70:73], v19 offset:8192
	ds_read_b128 v[74:77], v19 offset:12288
	ds_read_b128 v[78:81], v19 offset:16384
	ds_read_b128 v[82:85], v19 offset:20480
	ds_read_b128 v[86:89], v19 offset:24576
	ds_read_b128 v[90:93], v19 offset:28672
	ds_read_b128 v[94:97], v19
	ds_read_b128 v[98:101], v19 offset:32768
	s_waitcnt lgkmcnt(8)
	v_mov_b32_e32 v111, v66
	s_waitcnt lgkmcnt(7)
	v_mov_b32_e32 v112, v70
	s_waitcnt lgkmcnt(6)
	v_mov_b32_e32 v113, v74
	s_waitcnt lgkmcnt(1)
	v_mov_b32_e32 v110, v94
	v_mov_b32_e32 v114, v78
	v_mov_b32_e32 v115, v82
	v_mov_b32_e32 v116, v86
	v_mov_b32_e32 v117, v90
	v_mov_b32_e32 v66, v95
	v_mov_b32_e32 v74, v71
	v_mov_b32_e32 v82, v79
	v_mov_b32_e32 v90, v87
	v_mov_b32_e32 v70, v96
	v_mov_b32_e32 v71, v68
	v_mov_b32_e32 v78, v72
	v_mov_b32_e32 v79, v76
	v_mov_b32_e32 v86, v80
	v_mov_b32_e32 v87, v84
	v_mov_b32_e32 v94, v88
	v_mov_b32_e32 v95, v92
	v_mov_b32_e32 v68, v97
	v_mov_b32_e32 v76, v73
	v_mov_b32_e32 v84, v81
	v_mov_b32_e32 v92, v89
	v_add_u32_e32 v19, 16, v19
	s_waitcnt vmcnt(31)
	v_pk_fma_f32 v[42:43], v[138:139], v[110:111], v[42:43] op_sel_hi:[0,1,1]
	v_pk_fma_f32 v[44:45], v[138:139], v[112:113], v[44:45] op_sel_hi:[0,1,1]
	v_pk_fma_f32 v[46:47], v[138:139], v[114:115], v[46:47] op_sel_hi:[0,1,1]
	v_pk_fma_f32 v[48:49], v[138:139], v[116:117], v[48:49] op_sel_hi:[0,1,1]
	s_waitcnt lgkmcnt(0)
	v_fmac_f32_e32 v21, v138, v98
	s_waitcnt vmcnt(30)
	v_pk_fma_f32 v[42:43], v[138:139], v[66:67], v[42:43] op_sel:[1,0,0] op_sel_hi:[1,1,1]
	v_pk_fma_f32 v[44:45], v[138:139], v[74:75], v[44:45] op_sel:[1,0,0] op_sel_hi:[1,1,1]
	v_pk_fma_f32 v[46:47], v[138:139], v[82:83], v[46:47] op_sel:[1,0,0] op_sel_hi:[1,1,1]
	v_pk_fma_f32 v[48:49], v[138:139], v[90:91], v[48:49] op_sel:[1,0,0] op_sel_hi:[1,1,1]
	v_fmac_f32_e32 v21, v139, v99
	s_waitcnt vmcnt(29)
	v_pk_fma_f32 v[42:43], v[140:141], v[70:71], v[42:43] op_sel_hi:[0,1,1]
	v_pk_fma_f32 v[44:45], v[140:141], v[78:79], v[44:45] op_sel_hi:[0,1,1]
	v_pk_fma_f32 v[46:47], v[140:141], v[86:87], v[46:47] op_sel_hi:[0,1,1]
	v_pk_fma_f32 v[48:49], v[140:141], v[94:95], v[48:49] op_sel_hi:[0,1,1]
	v_fmac_f32_e32 v21, v140, v100
	s_waitcnt vmcnt(28)
	v_pk_fma_f32 v[42:43], v[140:141], v[68:69], v[42:43] op_sel:[1,0,0] op_sel_hi:[1,1,1]
	v_pk_fma_f32 v[44:45], v[140:141], v[76:77], v[44:45] op_sel:[1,0,0] op_sel_hi:[1,1,1]
	v_pk_fma_f32 v[46:47], v[140:141], v[84:85], v[46:47] op_sel:[1,0,0] op_sel_hi:[1,1,1]
	v_pk_fma_f32 v[48:49], v[140:141], v[92:93], v[48:49] op_sel:[1,0,0] op_sel_hi:[1,1,1]
	v_fmac_f32_e32 v21, v141, v101
	global_load_dword v138, v[150:151], off
	global_load_dword v139, v[152:153], off
	global_load_dword v140, v[154:155], off
	global_load_dword v141, v[156:157], off
	v_lshl_add_u64 v[150:151], v[150:151], 0, s[2:3]
	v_lshl_add_u64 v[152:153], v[152:153], 0, s[2:3]
	v_lshl_add_u64 v[154:155], v[154:155], 0, s[2:3]
	v_lshl_add_u64 v[156:157], v[156:157], 0, s[2:3]
	ds_read_b128 v[66:69], v19 offset:4096
	ds_read_b128 v[70:73], v19 offset:8192
	ds_read_b128 v[74:77], v19 offset:12288
	ds_read_b128 v[78:81], v19 offset:16384
	ds_read_b128 v[82:85], v19 offset:20480
	ds_read_b128 v[86:89], v19 offset:24576
	ds_read_b128 v[90:93], v19 offset:28672
	ds_read_b128 v[94:97], v19
	ds_read_b128 v[98:101], v19 offset:32768
	s_waitcnt lgkmcnt(8)
	v_mov_b32_e32 v111, v66
	s_waitcnt lgkmcnt(7)
	v_mov_b32_e32 v112, v70
	s_waitcnt lgkmcnt(6)
	v_mov_b32_e32 v113, v74
	s_waitcnt lgkmcnt(1)
	v_mov_b32_e32 v110, v94
	v_mov_b32_e32 v114, v78
	v_mov_b32_e32 v115, v82
	v_mov_b32_e32 v116, v86
	v_mov_b32_e32 v117, v90
	v_mov_b32_e32 v66, v95
	v_mov_b32_e32 v74, v71
	v_mov_b32_e32 v82, v79
	v_mov_b32_e32 v90, v87
	v_mov_b32_e32 v70, v96
	v_mov_b32_e32 v71, v68
	v_mov_b32_e32 v78, v72
	v_mov_b32_e32 v79, v76
	v_mov_b32_e32 v86, v80
	v_mov_b32_e32 v87, v84
	v_mov_b32_e32 v94, v88
	v_mov_b32_e32 v95, v92
	v_mov_b32_e32 v68, v97
	v_mov_b32_e32 v76, v73
	v_mov_b32_e32 v84, v81
	v_mov_b32_e32 v92, v89
	v_add_u32_e32 v19, 16, v19
	s_waitcnt vmcnt(31)
	v_pk_fma_f32 v[42:43], v[142:143], v[110:111], v[42:43] op_sel_hi:[0,1,1]
	v_pk_fma_f32 v[44:45], v[142:143], v[112:113], v[44:45] op_sel_hi:[0,1,1]
	v_pk_fma_f32 v[46:47], v[142:143], v[114:115], v[46:47] op_sel_hi:[0,1,1]
	v_pk_fma_f32 v[48:49], v[142:143], v[116:117], v[48:49] op_sel_hi:[0,1,1]
	s_waitcnt lgkmcnt(0)
	v_fmac_f32_e32 v21, v142, v98
	s_waitcnt vmcnt(30)
	v_pk_fma_f32 v[42:43], v[142:143], v[66:67], v[42:43] op_sel:[1,0,0] op_sel_hi:[1,1,1]
	v_pk_fma_f32 v[44:45], v[142:143], v[74:75], v[44:45] op_sel:[1,0,0] op_sel_hi:[1,1,1]
	v_pk_fma_f32 v[46:47], v[142:143], v[82:83], v[46:47] op_sel:[1,0,0] op_sel_hi:[1,1,1]
	v_pk_fma_f32 v[48:49], v[142:143], v[90:91], v[48:49] op_sel:[1,0,0] op_sel_hi:[1,1,1]
	v_fmac_f32_e32 v21, v143, v99
	s_waitcnt vmcnt(29)
	v_pk_fma_f32 v[42:43], v[144:145], v[70:71], v[42:43] op_sel_hi:[0,1,1]
	v_pk_fma_f32 v[44:45], v[144:145], v[78:79], v[44:45] op_sel_hi:[0,1,1]
	v_pk_fma_f32 v[46:47], v[144:145], v[86:87], v[46:47] op_sel_hi:[0,1,1]
	v_pk_fma_f32 v[48:49], v[144:145], v[94:95], v[48:49] op_sel_hi:[0,1,1]
	v_fmac_f32_e32 v21, v144, v100
	s_waitcnt vmcnt(28)
	v_pk_fma_f32 v[42:43], v[144:145], v[68:69], v[42:43] op_sel:[1,0,0] op_sel_hi:[1,1,1]
	v_pk_fma_f32 v[44:45], v[144:145], v[76:77], v[44:45] op_sel:[1,0,0] op_sel_hi:[1,1,1]
	v_pk_fma_f32 v[46:47], v[144:145], v[84:85], v[46:47] op_sel:[1,0,0] op_sel_hi:[1,1,1]
	v_pk_fma_f32 v[48:49], v[144:145], v[92:93], v[48:49] op_sel:[1,0,0] op_sel_hi:[1,1,1]
	v_fmac_f32_e32 v21, v145, v101
	global_load_dword v142, v[150:151], off
	global_load_dword v143, v[152:153], off
	global_load_dword v144, v[154:155], off
	global_load_dword v145, v[156:157], off
	v_lshl_add_u64 v[150:151], v[150:151], 0, s[2:3]
	v_lshl_add_u64 v[152:153], v[152:153], 0, s[2:3]
	v_lshl_add_u64 v[154:155], v[154:155], 0, s[2:3]
	v_lshl_add_u64 v[156:157], v[156:157], 0, s[2:3]
	ds_read_b128 v[66:69], v19 offset:4096
	ds_read_b128 v[70:73], v19 offset:8192
	ds_read_b128 v[74:77], v19 offset:12288
	ds_read_b128 v[78:81], v19 offset:16384
	ds_read_b128 v[82:85], v19 offset:20480
	ds_read_b128 v[86:89], v19 offset:24576
	ds_read_b128 v[90:93], v19 offset:28672
	ds_read_b128 v[94:97], v19
	ds_read_b128 v[98:101], v19 offset:32768
	s_waitcnt lgkmcnt(8)
	v_mov_b32_e32 v111, v66
	s_waitcnt lgkmcnt(7)
	v_mov_b32_e32 v112, v70
	s_waitcnt lgkmcnt(6)
	v_mov_b32_e32 v113, v74
	s_waitcnt lgkmcnt(1)
	v_mov_b32_e32 v110, v94
	v_mov_b32_e32 v114, v78
	v_mov_b32_e32 v115, v82
	v_mov_b32_e32 v116, v86
	v_mov_b32_e32 v117, v90
	v_mov_b32_e32 v66, v95
	v_mov_b32_e32 v74, v71
	v_mov_b32_e32 v82, v79
	v_mov_b32_e32 v90, v87
	v_mov_b32_e32 v70, v96
	v_mov_b32_e32 v71, v68
	v_mov_b32_e32 v78, v72
	v_mov_b32_e32 v79, v76
	v_mov_b32_e32 v86, v80
	v_mov_b32_e32 v87, v84
	v_mov_b32_e32 v94, v88
	v_mov_b32_e32 v95, v92
	v_mov_b32_e32 v68, v97
	v_mov_b32_e32 v76, v73
	v_mov_b32_e32 v84, v81
	v_mov_b32_e32 v92, v89
	v_add_u32_e32 v19, 16, v19
	s_waitcnt vmcnt(31)
	v_pk_fma_f32 v[42:43], v[146:147], v[110:111], v[42:43] op_sel_hi:[0,1,1]
	v_pk_fma_f32 v[44:45], v[146:147], v[112:113], v[44:45] op_sel_hi:[0,1,1]
	v_pk_fma_f32 v[46:47], v[146:147], v[114:115], v[46:47] op_sel_hi:[0,1,1]
	v_pk_fma_f32 v[48:49], v[146:147], v[116:117], v[48:49] op_sel_hi:[0,1,1]
	s_waitcnt lgkmcnt(0)
	v_fmac_f32_e32 v21, v146, v98
	s_waitcnt vmcnt(30)
	v_pk_fma_f32 v[42:43], v[146:147], v[66:67], v[42:43] op_sel:[1,0,0] op_sel_hi:[1,1,1]
	v_pk_fma_f32 v[44:45], v[146:147], v[74:75], v[44:45] op_sel:[1,0,0] op_sel_hi:[1,1,1]
	v_pk_fma_f32 v[46:47], v[146:147], v[82:83], v[46:47] op_sel:[1,0,0] op_sel_hi:[1,1,1]
	v_pk_fma_f32 v[48:49], v[146:147], v[90:91], v[48:49] op_sel:[1,0,0] op_sel_hi:[1,1,1]
	v_fmac_f32_e32 v21, v147, v99
	s_waitcnt vmcnt(29)
	v_pk_fma_f32 v[42:43], v[148:149], v[70:71], v[42:43] op_sel_hi:[0,1,1]
	v_pk_fma_f32 v[44:45], v[148:149], v[78:79], v[44:45] op_sel_hi:[0,1,1]
	v_pk_fma_f32 v[46:47], v[148:149], v[86:87], v[46:47] op_sel_hi:[0,1,1]
	v_pk_fma_f32 v[48:49], v[148:149], v[94:95], v[48:49] op_sel_hi:[0,1,1]
	v_fmac_f32_e32 v21, v148, v100
	s_waitcnt vmcnt(28)
	v_pk_fma_f32 v[42:43], v[148:149], v[68:69], v[42:43] op_sel:[1,0,0] op_sel_hi:[1,1,1]
	v_pk_fma_f32 v[44:45], v[148:149], v[76:77], v[44:45] op_sel:[1,0,0] op_sel_hi:[1,1,1]
	v_pk_fma_f32 v[46:47], v[148:149], v[84:85], v[46:47] op_sel:[1,0,0] op_sel_hi:[1,1,1]
	v_pk_fma_f32 v[48:49], v[148:149], v[92:93], v[48:49] op_sel:[1,0,0] op_sel_hi:[1,1,1]
	v_fmac_f32_e32 v21, v149, v101
	global_load_dword v146, v[150:151], off
	global_load_dword v147, v[152:153], off
	global_load_dword v148, v[154:155], off
	global_load_dword v149, v[156:157], off
	v_lshl_add_u64 v[150:151], v[150:151], 0, s[2:3]
	v_lshl_add_u64 v[152:153], v[152:153], 0, s[2:3]
	v_lshl_add_u64 v[154:155], v[154:155], 0, s[2:3]
	v_lshl_add_u64 v[156:157], v[156:157], 0, s[2:3]
	s_sub_u32 vcc_lo, vcc_lo, 1
	s_cmp_lg_u32 vcc_lo, 0
	s_cbranch_scc1 .Lmod_k
	ds_read_b128 v[66:69], v19 offset:4096
	ds_read_b128 v[70:73], v19 offset:8192
	ds_read_b128 v[74:77], v19 offset:12288
	ds_read_b128 v[78:81], v19 offset:16384
	ds_read_b128 v[82:85], v19 offset:20480
	ds_read_b128 v[86:89], v19 offset:24576
	ds_read_b128 v[90:93], v19 offset:28672
	ds_read_b128 v[94:97], v19
	ds_read_b128 v[98:101], v19 offset:32768
	s_waitcnt lgkmcnt(8)
	v_mov_b32_e32 v111, v66
	s_waitcnt lgkmcnt(7)
	v_mov_b32_e32 v112, v70
	s_waitcnt lgkmcnt(6)
	v_mov_b32_e32 v113, v74
	s_waitcnt lgkmcnt(1)
	v_mov_b32_e32 v110, v94
	v_mov_b32_e32 v114, v78
	v_mov_b32_e32 v115, v82
	v_mov_b32_e32 v116, v86
	v_mov_b32_e32 v117, v90
	v_mov_b32_e32 v66, v95
	v_mov_b32_e32 v74, v71
	v_mov_b32_e32 v82, v79
	v_mov_b32_e32 v90, v87
	v_mov_b32_e32 v70, v96
	v_mov_b32_e32 v71, v68
	v_mov_b32_e32 v78, v72
	v_mov_b32_e32 v79, v76
	v_mov_b32_e32 v86, v80
	v_mov_b32_e32 v87, v84
	v_mov_b32_e32 v94, v88
	v_mov_b32_e32 v95, v92
	v_mov_b32_e32 v68, v97
	v_mov_b32_e32 v76, v73
	v_mov_b32_e32 v84, v81
	v_mov_b32_e32 v92, v89
	v_add_u32_e32 v19, 16, v19
	s_waitcnt vmcnt(31)
	v_pk_fma_f32 v[42:43], v[118:119], v[110:111], v[42:43] op_sel_hi:[0,1,1]
	v_pk_fma_f32 v[44:45], v[118:119], v[112:113], v[44:45] op_sel_hi:[0,1,1]
	v_pk_fma_f32 v[46:47], v[118:119], v[114:115], v[46:47] op_sel_hi:[0,1,1]
	v_pk_fma_f32 v[48:49], v[118:119], v[116:117], v[48:49] op_sel_hi:[0,1,1]
	s_waitcnt lgkmcnt(0)
	v_fmac_f32_e32 v21, v118, v98
	s_waitcnt vmcnt(30)
	v_pk_fma_f32 v[42:43], v[118:119], v[66:67], v[42:43] op_sel:[1,0,0] op_sel_hi:[1,1,1]
	v_pk_fma_f32 v[44:45], v[118:119], v[74:75], v[44:45] op_sel:[1,0,0] op_sel_hi:[1,1,1]
	v_pk_fma_f32 v[46:47], v[118:119], v[82:83], v[46:47] op_sel:[1,0,0] op_sel_hi:[1,1,1]
	v_pk_fma_f32 v[48:49], v[118:119], v[90:91], v[48:49] op_sel:[1,0,0] op_sel_hi:[1,1,1]
	v_fmac_f32_e32 v21, v119, v99
	s_waitcnt vmcnt(29)
	v_pk_fma_f32 v[42:43], v[120:121], v[70:71], v[42:43] op_sel_hi:[0,1,1]
	v_pk_fma_f32 v[44:45], v[120:121], v[78:79], v[44:45] op_sel_hi:[0,1,1]
	v_pk_fma_f32 v[46:47], v[120:121], v[86:87], v[46:47] op_sel_hi:[0,1,1]
	v_pk_fma_f32 v[48:49], v[120:121], v[94:95], v[48:49] op_sel_hi:[0,1,1]
	v_fmac_f32_e32 v21, v120, v100
	s_waitcnt vmcnt(28)
	v_pk_fma_f32 v[42:43], v[120:121], v[68:69], v[42:43] op_sel:[1,0,0] op_sel_hi:[1,1,1]
	v_pk_fma_f32 v[44:45], v[120:121], v[76:77], v[44:45] op_sel:[1,0,0] op_sel_hi:[1,1,1]
	v_pk_fma_f32 v[46:47], v[120:121], v[84:85], v[46:47] op_sel:[1,0,0] op_sel_hi:[1,1,1]
	v_pk_fma_f32 v[48:49], v[120:121], v[92:93], v[48:49] op_sel:[1,0,0] op_sel_hi:[1,1,1]
	v_fmac_f32_e32 v21, v121, v101
	ds_read_b128 v[66:69], v19 offset:4096
	ds_read_b128 v[70:73], v19 offset:8192
	ds_read_b128 v[74:77], v19 offset:12288
	ds_read_b128 v[78:81], v19 offset:16384
	ds_read_b128 v[82:85], v19 offset:20480
	ds_read_b128 v[86:89], v19 offset:24576
	ds_read_b128 v[90:93], v19 offset:28672
	ds_read_b128 v[94:97], v19
	ds_read_b128 v[98:101], v19 offset:32768
	s_waitcnt lgkmcnt(8)
	v_mov_b32_e32 v111, v66
	s_waitcnt lgkmcnt(7)
	v_mov_b32_e32 v112, v70
	s_waitcnt lgkmcnt(6)
	v_mov_b32_e32 v113, v74
	s_waitcnt lgkmcnt(1)
	v_mov_b32_e32 v110, v94
	v_mov_b32_e32 v114, v78
	v_mov_b32_e32 v115, v82
	v_mov_b32_e32 v116, v86
	v_mov_b32_e32 v117, v90
	v_mov_b32_e32 v66, v95
	v_mov_b32_e32 v74, v71
	v_mov_b32_e32 v82, v79
	v_mov_b32_e32 v90, v87
	v_mov_b32_e32 v70, v96
	v_mov_b32_e32 v71, v68
	v_mov_b32_e32 v78, v72
	v_mov_b32_e32 v79, v76
	v_mov_b32_e32 v86, v80
	v_mov_b32_e32 v87, v84
	v_mov_b32_e32 v94, v88
	v_mov_b32_e32 v95, v92
	v_mov_b32_e32 v68, v97
	v_mov_b32_e32 v76, v73
	v_mov_b32_e32 v84, v81
	v_mov_b32_e32 v92, v89
	v_add_u32_e32 v19, 16, v19
	s_waitcnt vmcnt(27)
	v_pk_fma_f32 v[42:43], v[122:123], v[110:111], v[42:43] op_sel_hi:[0,1,1]
	v_pk_fma_f32 v[44:45], v[122:123], v[112:113], v[44:45] op_sel_hi:[0,1,1]
	v_pk_fma_f32 v[46:47], v[122:123], v[114:115], v[46:47] op_sel_hi:[0,1,1]
	v_pk_fma_f32 v[48:49], v[122:123], v[116:117], v[48:49] op_sel_hi:[0,1,1]
	s_waitcnt lgkmcnt(0)
	v_fmac_f32_e32 v21, v122, v98
	s_waitcnt vmcnt(26)
	v_pk_fma_f32 v[42:43], v[122:123], v[66:67], v[42:43] op_sel:[1,0,0] op_sel_hi:[1,1,1]
	v_pk_fma_f32 v[44:45], v[122:123], v[74:75], v[44:45] op_sel:[1,0,0] op_sel_hi:[1,1,1]
	v_pk_fma_f32 v[46:47], v[122:123], v[82:83], v[46:47] op_sel:[1,0,0] op_sel_hi:[1,1,1]
	v_pk_fma_f32 v[48:49], v[122:123], v[90:91], v[48:49] op_sel:[1,0,0] op_sel_hi:[1,1,1]
	v_fmac_f32_e32 v21, v123, v99
	s_waitcnt vmcnt(25)
	v_pk_fma_f32 v[42:43], v[124:125], v[70:71], v[42:43] op_sel_hi:[0,1,1]
	v_pk_fma_f32 v[44:45], v[124:125], v[78:79], v[44:45] op_sel_hi:[0,1,1]
	v_pk_fma_f32 v[46:47], v[124:125], v[86:87], v[46:47] op_sel_hi:[0,1,1]
	v_pk_fma_f32 v[48:49], v[124:125], v[94:95], v[48:49] op_sel_hi:[0,1,1]
	v_fmac_f32_e32 v21, v124, v100
	s_waitcnt vmcnt(24)
	v_pk_fma_f32 v[42:43], v[124:125], v[68:69], v[42:43] op_sel:[1,0,0] op_sel_hi:[1,1,1]
	v_pk_fma_f32 v[44:45], v[124:125], v[76:77], v[44:45] op_sel:[1,0,0] op_sel_hi:[1,1,1]
	v_pk_fma_f32 v[46:47], v[124:125], v[84:85], v[46:47] op_sel:[1,0,0] op_sel_hi:[1,1,1]
	v_pk_fma_f32 v[48:49], v[124:125], v[92:93], v[48:49] op_sel:[1,0,0] op_sel_hi:[1,1,1]
	v_fmac_f32_e32 v21, v125, v101
	ds_read_b128 v[66:69], v19 offset:4096
	ds_read_b128 v[70:73], v19 offset:8192
	ds_read_b128 v[74:77], v19 offset:12288
	ds_read_b128 v[78:81], v19 offset:16384
	ds_read_b128 v[82:85], v19 offset:20480
	ds_read_b128 v[86:89], v19 offset:24576
	ds_read_b128 v[90:93], v19 offset:28672
	ds_read_b128 v[94:97], v19
	ds_read_b128 v[98:101], v19 offset:32768
	s_waitcnt lgkmcnt(8)
	v_mov_b32_e32 v111, v66
	s_waitcnt lgkmcnt(7)
	v_mov_b32_e32 v112, v70
	s_waitcnt lgkmcnt(6)
	v_mov_b32_e32 v113, v74
	s_waitcnt lgkmcnt(1)
	v_mov_b32_e32 v110, v94
	v_mov_b32_e32 v114, v78
	v_mov_b32_e32 v115, v82
	v_mov_b32_e32 v116, v86
	v_mov_b32_e32 v117, v90
	v_mov_b32_e32 v66, v95
	v_mov_b32_e32 v74, v71
	v_mov_b32_e32 v82, v79
	v_mov_b32_e32 v90, v87
	v_mov_b32_e32 v70, v96
	v_mov_b32_e32 v71, v68
	v_mov_b32_e32 v78, v72
	v_mov_b32_e32 v79, v76
	v_mov_b32_e32 v86, v80
	v_mov_b32_e32 v87, v84
	v_mov_b32_e32 v94, v88
	v_mov_b32_e32 v95, v92
	v_mov_b32_e32 v68, v97
	v_mov_b32_e32 v76, v73
	v_mov_b32_e32 v84, v81
	v_mov_b32_e32 v92, v89
	v_add_u32_e32 v19, 16, v19
	s_waitcnt vmcnt(23)
	v_pk_fma_f32 v[42:43], v[126:127], v[110:111], v[42:43] op_sel_hi:[0,1,1]
	v_pk_fma_f32 v[44:45], v[126:127], v[112:113], v[44:45] op_sel_hi:[0,1,1]
	v_pk_fma_f32 v[46:47], v[126:127], v[114:115], v[46:47] op_sel_hi:[0,1,1]
	v_pk_fma_f32 v[48:49], v[126:127], v[116:117], v[48:49] op_sel_hi:[0,1,1]
	s_waitcnt lgkmcnt(0)
	v_fmac_f32_e32 v21, v126, v98
	s_waitcnt vmcnt(22)
	v_pk_fma_f32 v[42:43], v[126:127], v[66:67], v[42:43] op_sel:[1,0,0] op_sel_hi:[1,1,1]
	v_pk_fma_f32 v[44:45], v[126:127], v[74:75], v[44:45] op_sel:[1,0,0] op_sel_hi:[1,1,1]
	v_pk_fma_f32 v[46:47], v[126:127], v[82:83], v[46:47] op_sel:[1,0,0] op_sel_hi:[1,1,1]
	v_pk_fma_f32 v[48:49], v[126:127], v[90:91], v[48:49] op_sel:[1,0,0] op_sel_hi:[1,1,1]
	v_fmac_f32_e32 v21, v127, v99
	s_waitcnt vmcnt(21)
	v_pk_fma_f32 v[42:43], v[128:129], v[70:71], v[42:43] op_sel_hi:[0,1,1]
	v_pk_fma_f32 v[44:45], v[128:129], v[78:79], v[44:45] op_sel_hi:[0,1,1]
	v_pk_fma_f32 v[46:47], v[128:129], v[86:87], v[46:47] op_sel_hi:[0,1,1]
	v_pk_fma_f32 v[48:49], v[128:129], v[94:95], v[48:49] op_sel_hi:[0,1,1]
	v_fmac_f32_e32 v21, v128, v100
	s_waitcnt vmcnt(20)
	v_pk_fma_f32 v[42:43], v[128:129], v[68:69], v[42:43] op_sel:[1,0,0] op_sel_hi:[1,1,1]
	v_pk_fma_f32 v[44:45], v[128:129], v[76:77], v[44:45] op_sel:[1,0,0] op_sel_hi:[1,1,1]
	v_pk_fma_f32 v[46:47], v[128:129], v[84:85], v[46:47] op_sel:[1,0,0] op_sel_hi:[1,1,1]
	v_pk_fma_f32 v[48:49], v[128:129], v[92:93], v[48:49] op_sel:[1,0,0] op_sel_hi:[1,1,1]
	v_fmac_f32_e32 v21, v129, v101
	ds_read_b128 v[66:69], v19 offset:4096
	ds_read_b128 v[70:73], v19 offset:8192
	ds_read_b128 v[74:77], v19 offset:12288
	ds_read_b128 v[78:81], v19 offset:16384
	ds_read_b128 v[82:85], v19 offset:20480
	ds_read_b128 v[86:89], v19 offset:24576
	ds_read_b128 v[90:93], v19 offset:28672
	ds_read_b128 v[94:97], v19
	ds_read_b128 v[98:101], v19 offset:32768
	s_waitcnt lgkmcnt(8)
	v_mov_b32_e32 v111, v66
	s_waitcnt lgkmcnt(7)
	v_mov_b32_e32 v112, v70
	s_waitcnt lgkmcnt(6)
	v_mov_b32_e32 v113, v74
	s_waitcnt lgkmcnt(1)
	v_mov_b32_e32 v110, v94
	v_mov_b32_e32 v114, v78
	v_mov_b32_e32 v115, v82
	v_mov_b32_e32 v116, v86
	v_mov_b32_e32 v117, v90
	v_mov_b32_e32 v66, v95
	v_mov_b32_e32 v74, v71
	v_mov_b32_e32 v82, v79
	v_mov_b32_e32 v90, v87
	v_mov_b32_e32 v70, v96
	v_mov_b32_e32 v71, v68
	v_mov_b32_e32 v78, v72
	v_mov_b32_e32 v79, v76
	v_mov_b32_e32 v86, v80
	v_mov_b32_e32 v87, v84
	v_mov_b32_e32 v94, v88
	v_mov_b32_e32 v95, v92
	v_mov_b32_e32 v68, v97
	v_mov_b32_e32 v76, v73
	v_mov_b32_e32 v84, v81
	v_mov_b32_e32 v92, v89
	v_add_u32_e32 v19, 16, v19
	s_waitcnt vmcnt(19)
	v_pk_fma_f32 v[42:43], v[130:131], v[110:111], v[42:43] op_sel_hi:[0,1,1]
	v_pk_fma_f32 v[44:45], v[130:131], v[112:113], v[44:45] op_sel_hi:[0,1,1]
	v_pk_fma_f32 v[46:47], v[130:131], v[114:115], v[46:47] op_sel_hi:[0,1,1]
	v_pk_fma_f32 v[48:49], v[130:131], v[116:117], v[48:49] op_sel_hi:[0,1,1]
	s_waitcnt lgkmcnt(0)
	v_fmac_f32_e32 v21, v130, v98
	s_waitcnt vmcnt(18)
	v_pk_fma_f32 v[42:43], v[130:131], v[66:67], v[42:43] op_sel:[1,0,0] op_sel_hi:[1,1,1]
	v_pk_fma_f32 v[44:45], v[130:131], v[74:75], v[44:45] op_sel:[1,0,0] op_sel_hi:[1,1,1]
	v_pk_fma_f32 v[46:47], v[130:131], v[82:83], v[46:47] op_sel:[1,0,0] op_sel_hi:[1,1,1]
	v_pk_fma_f32 v[48:49], v[130:131], v[90:91], v[48:49] op_sel:[1,0,0] op_sel_hi:[1,1,1]
	v_fmac_f32_e32 v21, v131, v99
	s_waitcnt vmcnt(17)
	v_pk_fma_f32 v[42:43], v[132:133], v[70:71], v[42:43] op_sel_hi:[0,1,1]
	v_pk_fma_f32 v[44:45], v[132:133], v[78:79], v[44:45] op_sel_hi:[0,1,1]
	v_pk_fma_f32 v[46:47], v[132:133], v[86:87], v[46:47] op_sel_hi:[0,1,1]
	v_pk_fma_f32 v[48:49], v[132:133], v[94:95], v[48:49] op_sel_hi:[0,1,1]
	v_fmac_f32_e32 v21, v132, v100
	s_waitcnt vmcnt(16)
	v_pk_fma_f32 v[42:43], v[132:133], v[68:69], v[42:43] op_sel:[1,0,0] op_sel_hi:[1,1,1]
	v_pk_fma_f32 v[44:45], v[132:133], v[76:77], v[44:45] op_sel:[1,0,0] op_sel_hi:[1,1,1]
	v_pk_fma_f32 v[46:47], v[132:133], v[84:85], v[46:47] op_sel:[1,0,0] op_sel_hi:[1,1,1]
	v_pk_fma_f32 v[48:49], v[132:133], v[92:93], v[48:49] op_sel:[1,0,0] op_sel_hi:[1,1,1]
	v_fmac_f32_e32 v21, v133, v101
	ds_read_b128 v[66:69], v19 offset:4096
	ds_read_b128 v[70:73], v19 offset:8192
	ds_read_b128 v[74:77], v19 offset:12288
	ds_read_b128 v[78:81], v19 offset:16384
	ds_read_b128 v[82:85], v19 offset:20480
	ds_read_b128 v[86:89], v19 offset:24576
	ds_read_b128 v[90:93], v19 offset:28672
	ds_read_b128 v[94:97], v19
	ds_read_b128 v[98:101], v19 offset:32768
	s_waitcnt lgkmcnt(8)
	v_mov_b32_e32 v111, v66
	s_waitcnt lgkmcnt(7)
	v_mov_b32_e32 v112, v70
	s_waitcnt lgkmcnt(6)
	v_mov_b32_e32 v113, v74
	s_waitcnt lgkmcnt(1)
	v_mov_b32_e32 v110, v94
	v_mov_b32_e32 v114, v78
	v_mov_b32_e32 v115, v82
	v_mov_b32_e32 v116, v86
	v_mov_b32_e32 v117, v90
	v_mov_b32_e32 v66, v95
	v_mov_b32_e32 v74, v71
	v_mov_b32_e32 v82, v79
	v_mov_b32_e32 v90, v87
	v_mov_b32_e32 v70, v96
	v_mov_b32_e32 v71, v68
	v_mov_b32_e32 v78, v72
	v_mov_b32_e32 v79, v76
	v_mov_b32_e32 v86, v80
	v_mov_b32_e32 v87, v84
	v_mov_b32_e32 v94, v88
	v_mov_b32_e32 v95, v92
	v_mov_b32_e32 v68, v97
	v_mov_b32_e32 v76, v73
	v_mov_b32_e32 v84, v81
	v_mov_b32_e32 v92, v89
	v_add_u32_e32 v19, 16, v19
	s_waitcnt vmcnt(15)
	v_pk_fma_f32 v[42:43], v[134:135], v[110:111], v[42:43] op_sel_hi:[0,1,1]
	v_pk_fma_f32 v[44:45], v[134:135], v[112:113], v[44:45] op_sel_hi:[0,1,1]
	v_pk_fma_f32 v[46:47], v[134:135], v[114:115], v[46:47] op_sel_hi:[0,1,1]
	v_pk_fma_f32 v[48:49], v[134:135], v[116:117], v[48:49] op_sel_hi:[0,1,1]
	s_waitcnt lgkmcnt(0)
	v_fmac_f32_e32 v21, v134, v98
	s_waitcnt vmcnt(14)
	v_pk_fma_f32 v[42:43], v[134:135], v[66:67], v[42:43] op_sel:[1,0,0] op_sel_hi:[1,1,1]
	v_pk_fma_f32 v[44:45], v[134:135], v[74:75], v[44:45] op_sel:[1,0,0] op_sel_hi:[1,1,1]
	v_pk_fma_f32 v[46:47], v[134:135], v[82:83], v[46:47] op_sel:[1,0,0] op_sel_hi:[1,1,1]
	v_pk_fma_f32 v[48:49], v[134:135], v[90:91], v[48:49] op_sel:[1,0,0] op_sel_hi:[1,1,1]
	v_fmac_f32_e32 v21, v135, v99
	s_waitcnt vmcnt(13)
	v_pk_fma_f32 v[42:43], v[136:137], v[70:71], v[42:43] op_sel_hi:[0,1,1]
	v_pk_fma_f32 v[44:45], v[136:137], v[78:79], v[44:45] op_sel_hi:[0,1,1]
	v_pk_fma_f32 v[46:47], v[136:137], v[86:87], v[46:47] op_sel_hi:[0,1,1]
	v_pk_fma_f32 v[48:49], v[136:137], v[94:95], v[48:49] op_sel_hi:[0,1,1]
	v_fmac_f32_e32 v21, v136, v100
	s_waitcnt vmcnt(12)
	v_pk_fma_f32 v[42:43], v[136:137], v[68:69], v[42:43] op_sel:[1,0,0] op_sel_hi:[1,1,1]
	v_pk_fma_f32 v[44:45], v[136:137], v[76:77], v[44:45] op_sel:[1,0,0] op_sel_hi:[1,1,1]
	v_pk_fma_f32 v[46:47], v[136:137], v[84:85], v[46:47] op_sel:[1,0,0] op_sel_hi:[1,1,1]
	v_pk_fma_f32 v[48:49], v[136:137], v[92:93], v[48:49] op_sel:[1,0,0] op_sel_hi:[1,1,1]
	v_fmac_f32_e32 v21, v137, v101
	ds_read_b128 v[66:69], v19 offset:4096
	ds_read_b128 v[70:73], v19 offset:8192
	ds_read_b128 v[74:77], v19 offset:12288
	ds_read_b128 v[78:81], v19 offset:16384
	ds_read_b128 v[82:85], v19 offset:20480
	ds_read_b128 v[86:89], v19 offset:24576
	ds_read_b128 v[90:93], v19 offset:28672
	ds_read_b128 v[94:97], v19
	ds_read_b128 v[98:101], v19 offset:32768
	s_waitcnt lgkmcnt(8)
	v_mov_b32_e32 v111, v66
	s_waitcnt lgkmcnt(7)
	v_mov_b32_e32 v112, v70
	s_waitcnt lgkmcnt(6)
	v_mov_b32_e32 v113, v74
	s_waitcnt lgkmcnt(1)
	v_mov_b32_e32 v110, v94
	v_mov_b32_e32 v114, v78
	v_mov_b32_e32 v115, v82
	v_mov_b32_e32 v116, v86
	v_mov_b32_e32 v117, v90
	v_mov_b32_e32 v66, v95
	v_mov_b32_e32 v74, v71
	v_mov_b32_e32 v82, v79
	v_mov_b32_e32 v90, v87
	v_mov_b32_e32 v70, v96
	v_mov_b32_e32 v71, v68
	v_mov_b32_e32 v78, v72
	v_mov_b32_e32 v79, v76
	v_mov_b32_e32 v86, v80
	v_mov_b32_e32 v87, v84
	v_mov_b32_e32 v94, v88
	v_mov_b32_e32 v95, v92
	v_mov_b32_e32 v68, v97
	v_mov_b32_e32 v76, v73
	v_mov_b32_e32 v84, v81
	v_mov_b32_e32 v92, v89
	v_add_u32_e32 v19, 16, v19
	s_waitcnt vmcnt(11)
	v_pk_fma_f32 v[42:43], v[138:139], v[110:111], v[42:43] op_sel_hi:[0,1,1]
	v_pk_fma_f32 v[44:45], v[138:139], v[112:113], v[44:45] op_sel_hi:[0,1,1]
	v_pk_fma_f32 v[46:47], v[138:139], v[114:115], v[46:47] op_sel_hi:[0,1,1]
	v_pk_fma_f32 v[48:49], v[138:139], v[116:117], v[48:49] op_sel_hi:[0,1,1]
	s_waitcnt lgkmcnt(0)
	v_fmac_f32_e32 v21, v138, v98
	s_waitcnt vmcnt(10)
	v_pk_fma_f32 v[42:43], v[138:139], v[66:67], v[42:43] op_sel:[1,0,0] op_sel_hi:[1,1,1]
	v_pk_fma_f32 v[44:45], v[138:139], v[74:75], v[44:45] op_sel:[1,0,0] op_sel_hi:[1,1,1]
	v_pk_fma_f32 v[46:47], v[138:139], v[82:83], v[46:47] op_sel:[1,0,0] op_sel_hi:[1,1,1]
	v_pk_fma_f32 v[48:49], v[138:139], v[90:91], v[48:49] op_sel:[1,0,0] op_sel_hi:[1,1,1]
	v_fmac_f32_e32 v21, v139, v99
	s_waitcnt vmcnt(9)
	v_pk_fma_f32 v[42:43], v[140:141], v[70:71], v[42:43] op_sel_hi:[0,1,1]
	v_pk_fma_f32 v[44:45], v[140:141], v[78:79], v[44:45] op_sel_hi:[0,1,1]
	v_pk_fma_f32 v[46:47], v[140:141], v[86:87], v[46:47] op_sel_hi:[0,1,1]
	v_pk_fma_f32 v[48:49], v[140:141], v[94:95], v[48:49] op_sel_hi:[0,1,1]
	v_fmac_f32_e32 v21, v140, v100
	s_waitcnt vmcnt(8)
	v_pk_fma_f32 v[42:43], v[140:141], v[68:69], v[42:43] op_sel:[1,0,0] op_sel_hi:[1,1,1]
	v_pk_fma_f32 v[44:45], v[140:141], v[76:77], v[44:45] op_sel:[1,0,0] op_sel_hi:[1,1,1]
	v_pk_fma_f32 v[46:47], v[140:141], v[84:85], v[46:47] op_sel:[1,0,0] op_sel_hi:[1,1,1]
	v_pk_fma_f32 v[48:49], v[140:141], v[92:93], v[48:49] op_sel:[1,0,0] op_sel_hi:[1,1,1]
	v_fmac_f32_e32 v21, v141, v101
	ds_read_b128 v[66:69], v19 offset:4096
	ds_read_b128 v[70:73], v19 offset:8192
	ds_read_b128 v[74:77], v19 offset:12288
	ds_read_b128 v[78:81], v19 offset:16384
	ds_read_b128 v[82:85], v19 offset:20480
	ds_read_b128 v[86:89], v19 offset:24576
	ds_read_b128 v[90:93], v19 offset:28672
	ds_read_b128 v[94:97], v19
	ds_read_b128 v[98:101], v19 offset:32768
	s_waitcnt lgkmcnt(8)
	v_mov_b32_e32 v111, v66
	s_waitcnt lgkmcnt(7)
	v_mov_b32_e32 v112, v70
	s_waitcnt lgkmcnt(6)
	v_mov_b32_e32 v113, v74
	s_waitcnt lgkmcnt(1)
	v_mov_b32_e32 v110, v94
	v_mov_b32_e32 v114, v78
	v_mov_b32_e32 v115, v82
	v_mov_b32_e32 v116, v86
	v_mov_b32_e32 v117, v90
	v_mov_b32_e32 v66, v95
	v_mov_b32_e32 v74, v71
	v_mov_b32_e32 v82, v79
	v_mov_b32_e32 v90, v87
	v_mov_b32_e32 v70, v96
	v_mov_b32_e32 v71, v68
	v_mov_b32_e32 v78, v72
	v_mov_b32_e32 v79, v76
	v_mov_b32_e32 v86, v80
	v_mov_b32_e32 v87, v84
	v_mov_b32_e32 v94, v88
	v_mov_b32_e32 v95, v92
	v_mov_b32_e32 v68, v97
	v_mov_b32_e32 v76, v73
	v_mov_b32_e32 v84, v81
	v_mov_b32_e32 v92, v89
	v_add_u32_e32 v19, 16, v19
	s_waitcnt vmcnt(7)
	v_pk_fma_f32 v[42:43], v[142:143], v[110:111], v[42:43] op_sel_hi:[0,1,1]
	v_pk_fma_f32 v[44:45], v[142:143], v[112:113], v[44:45] op_sel_hi:[0,1,1]
	v_pk_fma_f32 v[46:47], v[142:143], v[114:115], v[46:47] op_sel_hi:[0,1,1]
	v_pk_fma_f32 v[48:49], v[142:143], v[116:117], v[48:49] op_sel_hi:[0,1,1]
	s_waitcnt lgkmcnt(0)
	v_fmac_f32_e32 v21, v142, v98
	s_waitcnt vmcnt(6)
	v_pk_fma_f32 v[42:43], v[142:143], v[66:67], v[42:43] op_sel:[1,0,0] op_sel_hi:[1,1,1]
	v_pk_fma_f32 v[44:45], v[142:143], v[74:75], v[44:45] op_sel:[1,0,0] op_sel_hi:[1,1,1]
	v_pk_fma_f32 v[46:47], v[142:143], v[82:83], v[46:47] op_sel:[1,0,0] op_sel_hi:[1,1,1]
	v_pk_fma_f32 v[48:49], v[142:143], v[90:91], v[48:49] op_sel:[1,0,0] op_sel_hi:[1,1,1]
	v_fmac_f32_e32 v21, v143, v99
	s_waitcnt vmcnt(5)
	v_pk_fma_f32 v[42:43], v[144:145], v[70:71], v[42:43] op_sel_hi:[0,1,1]
	v_pk_fma_f32 v[44:45], v[144:145], v[78:79], v[44:45] op_sel_hi:[0,1,1]
	v_pk_fma_f32 v[46:47], v[144:145], v[86:87], v[46:47] op_sel_hi:[0,1,1]
	v_pk_fma_f32 v[48:49], v[144:145], v[94:95], v[48:49] op_sel_hi:[0,1,1]
	v_fmac_f32_e32 v21, v144, v100
	s_waitcnt vmcnt(4)
	v_pk_fma_f32 v[42:43], v[144:145], v[68:69], v[42:43] op_sel:[1,0,0] op_sel_hi:[1,1,1]
	v_pk_fma_f32 v[44:45], v[144:145], v[76:77], v[44:45] op_sel:[1,0,0] op_sel_hi:[1,1,1]
	v_pk_fma_f32 v[46:47], v[144:145], v[84:85], v[46:47] op_sel:[1,0,0] op_sel_hi:[1,1,1]
	v_pk_fma_f32 v[48:49], v[144:145], v[92:93], v[48:49] op_sel:[1,0,0] op_sel_hi:[1,1,1]
	v_fmac_f32_e32 v21, v145, v101
	ds_read_b128 v[66:69], v19 offset:4096
	ds_read_b128 v[70:73], v19 offset:8192
	ds_read_b128 v[74:77], v19 offset:12288
	ds_read_b128 v[78:81], v19 offset:16384
	ds_read_b128 v[82:85], v19 offset:20480
	ds_read_b128 v[86:89], v19 offset:24576
	ds_read_b128 v[90:93], v19 offset:28672
	ds_read_b128 v[94:97], v19
	ds_read_b128 v[98:101], v19 offset:32768
	s_waitcnt lgkmcnt(8)
	v_mov_b32_e32 v111, v66
	s_waitcnt lgkmcnt(7)
	v_mov_b32_e32 v112, v70
	s_waitcnt lgkmcnt(6)
	v_mov_b32_e32 v113, v74
	s_waitcnt lgkmcnt(1)
	v_mov_b32_e32 v110, v94
	v_mov_b32_e32 v114, v78
	v_mov_b32_e32 v115, v82
	v_mov_b32_e32 v116, v86
	v_mov_b32_e32 v117, v90
	v_mov_b32_e32 v66, v95
	v_mov_b32_e32 v74, v71
	v_mov_b32_e32 v82, v79
	v_mov_b32_e32 v90, v87
	v_mov_b32_e32 v70, v96
	v_mov_b32_e32 v71, v68
	v_mov_b32_e32 v78, v72
	v_mov_b32_e32 v79, v76
	v_mov_b32_e32 v86, v80
	v_mov_b32_e32 v87, v84
	v_mov_b32_e32 v94, v88
	v_mov_b32_e32 v95, v92
	v_mov_b32_e32 v68, v97
	v_mov_b32_e32 v76, v73
	v_mov_b32_e32 v84, v81
	v_mov_b32_e32 v92, v89
	v_add_u32_e32 v19, 16, v19
	s_waitcnt vmcnt(3)
	v_pk_fma_f32 v[42:43], v[146:147], v[110:111], v[42:43] op_sel_hi:[0,1,1]
	v_pk_fma_f32 v[44:45], v[146:147], v[112:113], v[44:45] op_sel_hi:[0,1,1]
	v_pk_fma_f32 v[46:47], v[146:147], v[114:115], v[46:47] op_sel_hi:[0,1,1]
	v_pk_fma_f32 v[48:49], v[146:147], v[116:117], v[48:49] op_sel_hi:[0,1,1]
	s_waitcnt lgkmcnt(0)
	v_fmac_f32_e32 v21, v146, v98
	s_waitcnt vmcnt(2)
	v_pk_fma_f32 v[42:43], v[146:147], v[66:67], v[42:43] op_sel:[1,0,0] op_sel_hi:[1,1,1]
	v_pk_fma_f32 v[44:45], v[146:147], v[74:75], v[44:45] op_sel:[1,0,0] op_sel_hi:[1,1,1]
	v_pk_fma_f32 v[46:47], v[146:147], v[82:83], v[46:47] op_sel:[1,0,0] op_sel_hi:[1,1,1]
	v_pk_fma_f32 v[48:49], v[146:147], v[90:91], v[48:49] op_sel:[1,0,0] op_sel_hi:[1,1,1]
	v_fmac_f32_e32 v21, v147, v99
	s_waitcnt vmcnt(1)
	v_pk_fma_f32 v[42:43], v[148:149], v[70:71], v[42:43] op_sel_hi:[0,1,1]
	v_pk_fma_f32 v[44:45], v[148:149], v[78:79], v[44:45] op_sel_hi:[0,1,1]
	v_pk_fma_f32 v[46:47], v[148:149], v[86:87], v[46:47] op_sel_hi:[0,1,1]
	v_pk_fma_f32 v[48:49], v[148:149], v[94:95], v[48:49] op_sel_hi:[0,1,1]
	v_fmac_f32_e32 v21, v148, v100
	s_waitcnt vmcnt(0)
	v_pk_fma_f32 v[42:43], v[148:149], v[68:69], v[42:43] op_sel:[1,0,0] op_sel_hi:[1,1,1]
	v_pk_fma_f32 v[44:45], v[148:149], v[76:77], v[44:45] op_sel:[1,0,0] op_sel_hi:[1,1,1]
	v_pk_fma_f32 v[46:47], v[148:149], v[84:85], v[46:47] op_sel:[1,0,0] op_sel_hi:[1,1,1]
	v_pk_fma_f32 v[48:49], v[148:149], v[92:93], v[48:49] op_sel:[1,0,0] op_sel_hi:[1,1,1]
	v_fmac_f32_e32 v21, v149, v101
	v_mad_u64_u32 v[38:39], s[2:3], v2, s46, v[38:39]
	v_or_b32_e32 v38, v38, v53
	v_readlane_b32 s52, v241, 1
	v_mad_u64_u32 v[40:41], s[2:3], v2, 9, v[8:9]
	v_ashrrev_i32_e32 v39, 31, v38
	v_readlane_b32 s54, v241, 3
	v_readlane_b32 s55, v241, 4
	v_mad_i64_i32 v[36:37], s[2:3], v40, s38, v[36:37]
	ds_write2st64_b32 v54, v42, v43 offset0:144 offset1:145
	ds_write2st64_b32 v54, v44, v45 offset0:146 offset1:147
	ds_write2st64_b32 v54, v46, v47 offset0:148 offset1:149
	ds_write2st64_b32 v54, v48, v49 offset0:150 offset1:151
	ds_write_b32 v54, v21 offset:38912
	v_lshl_add_u64 v[38:39], v[38:39], 2, s[54:55]
	v_lshl_add_u64 v[36:37], v[16:17], 0, v[36:37]
	s_mov_b64 s[2:3], 0
	v_mov_b32_e32 v2, v60
	v_mov_b32_e32 v19, v59
	v_mov_b32_e32 v21, v58
	s_waitcnt lgkmcnt(0)
	s_barrier
	v_readlane_b32 s53, v241, 2
	v_readlane_b32 s56, v241, 5
	v_readlane_b32 s57, v241, 6
	v_readlane_b32 s58, v241, 7
	v_readlane_b32 s59, v241, 8
	v_readlane_b32 s60, v241, 9
	v_readlane_b32 s61, v241, 10
	v_readlane_b32 s62, v241, 11
	v_readlane_b32 s63, v241, 12
	v_readlane_b32 s64, v241, 13
	v_readlane_b32 s65, v241, 14
	v_readlane_b32 s66, v241, 15
	v_readlane_b32 s67, v241, 16
